# GEMM K-loops: shorter MFMA hand-over between half-workgroups (priority raise before the block barrier, redundant LDS wait after it removed, priority drop after the end barrier)
# speedup vs baseline: 1.0050x; 1.0050x over previous
.LBB0_565:
	s_ashr_i32 s25, s24, 31
	s_lshl_b64 s[26:27], s[24:25], 19
	s_add_u32 s26, s84, s26
	s_addc_u32 s27, s85, s27
	s_and_b64 s[28:29], s[10:11], exec
	s_cselect_b32 s3, s27, s1
	s_cselect_b32 s25, s26, s0
	s_ashr_i32 s23, s22, 31
	s_lshl_b64 s[28:29], s[22:23], 19
	s_add_u32 s28, s37, s28
	s_addc_u32 s29, s38, s29
	s_and_b64 s[34:35], s[10:11], exec
	s_cselect_b32 s23, s29, s31
	s_cselect_b32 s48, s28, s30
	s_add_u32 s0, s0, 0x40080
	s_addc_u32 s1, s1, 0
	s_add_u32 s49, s30, 0x100
	s_addc_u32 s50, s31, 0
	s_mov_b32 s51, -2
	s_waitcnt lgkmcnt(0)
	s_add_u32 s30, s0, 0xfffc0080
	s_addc_u32 s31, s1, -1
	s_add_i32 s52, 0, 0x10000
	s_cmp_eq_u32 s51, 12
	s_cselect_b32 s35, s3, s31
	s_cselect_b32 s34, s25, s30
	s_cselect_b32 s31, s23, s50
	s_cselect_b32 s30, s48, s49
	s_add_i32 s54, 0, 0x14000
	v_add_u32_e32 v158, s52, v199
	v_add_u32_e32 v174, s54, v199
	ds_read_b128 v[134:137], v158
	ds_read_b128 v[150:153], v158 offset:1024
	ds_read_b128 v[154:157], v158 offset:2048
	ds_read_b128 v[158:161], v158 offset:3072
	ds_read_b128 v[162:165], v174
	ds_read_b128 v[166:169], v174 offset:1024
	ds_read_b128 v[170:173], v174 offset:2048
	ds_read_b128 v[182:185], v174 offset:3072
	v_lshl_add_u64 v[174:175], s[0:1], 0, v[146:147]
	s_add_i32 m0, s39, 0xc000
	ds_read_b128 v[186:189], v201
	ds_read_b128 v[202:205], v201 offset:1024
	ds_read_b128 v[206:209], v201 offset:2048
	ds_read_b128 v[210:213], v201 offset:3072
	ds_read_b128 v[214:217], v201 offset:4096
	ds_read_b128 v[218:221], v201 offset:5120
	ds_read_b128 v[222:225], v201 offset:6144
	ds_read_b128 v[226:229], v201 offset:7168
	global_load_lds_dwordx4 v[174:175], off
	v_lshl_add_u64 v[174:175], s[0:1], 0, v[148:149]
	s_add_i32 m0, s39, 0xe000
	s_nop 0
	global_load_lds_dwordx4 v[174:175], off
	s_waitcnt vmcnt(8)
	s_waitcnt lgkmcnt(0)
	s_setprio 1
	s_barrier
	v_mfma_f32_16x16x32_bf16 v[130:133], v[134:137], v[186:189], 0
	v_mfma_f32_16x16x32_bf16 v[130:133], v[150:153], v[202:205], v[130:133]
	v_mfma_f32_16x16x32_bf16 v[126:129], v[154:157], v[186:189], 0
	v_mfma_f32_16x16x32_bf16 v[126:129], v[158:161], v[202:205], v[126:129]
	v_mfma_f32_16x16x32_bf16 v[114:117], v[134:137], v[206:209], 0
	v_mfma_f32_16x16x32_bf16 v[114:117], v[150:153], v[210:213], v[114:117]
	v_mfma_f32_16x16x32_bf16 v[110:113], v[154:157], v[206:209], 0
	v_mfma_f32_16x16x32_bf16 v[110:113], v[158:161], v[210:213], v[110:113]
	v_mfma_f32_16x16x32_bf16 v[98:101], v[134:137], v[214:217], 0
	v_mfma_f32_16x16x32_bf16 v[98:101], v[150:153], v[218:221], v[98:101]
	v_mfma_f32_16x16x32_bf16 v[94:97], v[154:157], v[214:217], 0
	v_mfma_f32_16x16x32_bf16 v[94:97], v[158:161], v[218:221], v[94:97]
	v_mfma_f32_16x16x32_bf16 v[82:85], v[134:137], v[222:225], 0
	v_mfma_f32_16x16x32_bf16 v[82:85], v[150:153], v[226:229], v[82:85]
	v_mfma_f32_16x16x32_bf16 v[78:81], v[154:157], v[222:225], 0
	v_mfma_f32_16x16x32_bf16 v[78:81], v[158:161], v[226:229], v[78:81]
	v_mfma_f32_16x16x32_bf16 v[122:125], v[162:165], v[186:189], 0
	v_mfma_f32_16x16x32_bf16 v[122:125], v[166:169], v[202:205], v[122:125]
	v_mfma_f32_16x16x32_bf16 v[118:121], v[170:173], v[186:189], 0
	v_mfma_f32_16x16x32_bf16 v[118:121], v[182:185], v[202:205], v[118:121]
	v_mfma_f32_16x16x32_bf16 v[106:109], v[162:165], v[206:209], 0
	v_mfma_f32_16x16x32_bf16 v[106:109], v[166:169], v[210:213], v[106:109]
	v_mfma_f32_16x16x32_bf16 v[102:105], v[170:173], v[206:209], 0
	v_mfma_f32_16x16x32_bf16 v[102:105], v[182:185], v[210:213], v[102:105]
	v_mfma_f32_16x16x32_bf16 v[90:93], v[162:165], v[214:217], 0
	v_mfma_f32_16x16x32_bf16 v[90:93], v[166:169], v[218:221], v[90:93]
	v_mfma_f32_16x16x32_bf16 v[86:89], v[170:173], v[214:217], 0
	v_mfma_f32_16x16x32_bf16 v[86:89], v[182:185], v[218:221], v[86:89]
	v_mfma_f32_16x16x32_bf16 v[74:77], v[162:165], v[222:225], 0
	v_mfma_f32_16x16x32_bf16 v[74:77], v[166:169], v[226:229], v[74:77]
	v_mfma_f32_16x16x32_bf16 v[70:73], v[170:173], v[222:225], 0
	v_mfma_f32_16x16x32_bf16 v[70:73], v[182:185], v[226:229], v[70:73]
	s_barrier
	s_setprio 0
	s_add_i32 s52, s52, s36
	v_lshl_add_u64 v[174:175], s[30:31], 0, v[0:1]
	s_mov_b32 m0, s52
	ds_read_b128 v[186:189], v201 offset:16384
	ds_read_b128 v[202:205], v201 offset:17408
	ds_read_b128 v[206:209], v201 offset:18432
	ds_read_b128 v[210:213], v201 offset:19456
	ds_read_b128 v[214:217], v201 offset:20480
	ds_read_b128 v[218:221], v201 offset:21504
	ds_read_b128 v[222:225], v201 offset:22528
	ds_read_b128 v[226:229], v201 offset:23552
	global_load_lds_dwordx4 v[174:175], off
	s_add_i32 m0, s52, 0x2000
	s_add_u32 s52, s30, 0x40000
	v_lshl_add_u64 v[190:191], s[30:31], 0, v[14:15]
	s_addc_u32 s53, s31, 0
	s_add_i32 s54, s54, s36
	global_load_lds_dwordx4 v[190:191], off
	v_lshl_add_u64 v[230:231], s[52:53], 0, v[0:1]
	s_mov_b32 m0, s54
	v_lshl_add_u64 v[232:233], s[34:35], 0, v[138:139]
	global_load_lds_dwordx4 v[230:231], off
	v_lshl_add_u64 v[230:231], s[52:53], 0, v[14:15]
	s_add_i32 m0, s54, 0x2000
	s_nop 0
	global_load_lds_dwordx4 v[230:231], off
	v_lshl_add_u64 v[230:231], s[34:35], 0, v[140:141]
	s_mov_b32 m0, s39
	s_nop 0
	global_load_lds_dwordx4 v[230:231], off
	s_mov_b32 m0, s40
	s_nop 0
	global_load_lds_dwordx4 v[232:233], off
	s_waitcnt vmcnt(8)
	s_waitcnt lgkmcnt(0)
	s_setprio 1
	s_barrier
	v_mfma_f32_16x16x32_bf16 v[66:69], v[134:137], v[186:189], 0
	v_mfma_f32_16x16x32_bf16 v[66:69], v[150:153], v[202:205], v[66:69]
	v_mfma_f32_16x16x32_bf16 v[62:65], v[154:157], v[186:189], 0
	v_mfma_f32_16x16x32_bf16 v[62:65], v[158:161], v[202:205], v[62:65]
	v_mfma_f32_16x16x32_bf16 v[50:53], v[134:137], v[206:209], 0
	v_mfma_f32_16x16x32_bf16 v[50:53], v[150:153], v[210:213], v[50:53]
	v_mfma_f32_16x16x32_bf16 v[46:49], v[154:157], v[206:209], 0
	v_mfma_f32_16x16x32_bf16 v[46:49], v[158:161], v[210:213], v[46:49]
	v_mfma_f32_16x16x32_bf16 v[34:37], v[134:137], v[214:217], 0
	v_mfma_f32_16x16x32_bf16 v[34:37], v[150:153], v[218:221], v[34:37]
	v_mfma_f32_16x16x32_bf16 v[30:33], v[154:157], v[214:217], 0
	v_mfma_f32_16x16x32_bf16 v[30:33], v[158:161], v[218:221], v[30:33]
	v_mfma_f32_16x16x32_bf16 v[18:21], v[134:137], v[222:225], 0
	v_mfma_f32_16x16x32_bf16 v[18:21], v[150:153], v[226:229], v[18:21]
	v_mfma_f32_16x16x32_bf16 v[10:13], v[154:157], v[222:225], 0
	v_mfma_f32_16x16x32_bf16 v[10:13], v[158:161], v[226:229], v[10:13]
	v_mfma_f32_16x16x32_bf16 v[58:61], v[162:165], v[186:189], 0
	v_mfma_f32_16x16x32_bf16 v[58:61], v[166:169], v[202:205], v[58:61]
	v_mfma_f32_16x16x32_bf16 v[54:57], v[170:173], v[186:189], 0
	v_mfma_f32_16x16x32_bf16 v[54:57], v[182:185], v[202:205], v[54:57]
	v_mfma_f32_16x16x32_bf16 v[42:45], v[162:165], v[206:209], 0
	v_mfma_f32_16x16x32_bf16 v[42:45], v[166:169], v[210:213], v[42:45]
	v_mfma_f32_16x16x32_bf16 v[38:41], v[170:173], v[206:209], 0
	v_mfma_f32_16x16x32_bf16 v[38:41], v[182:185], v[210:213], v[38:41]
	v_mfma_f32_16x16x32_bf16 v[26:29], v[162:165], v[214:217], 0
	v_mfma_f32_16x16x32_bf16 v[26:29], v[166:169], v[218:221], v[26:29]
	v_mfma_f32_16x16x32_bf16 v[22:25], v[170:173], v[214:217], 0
	v_mfma_f32_16x16x32_bf16 v[22:25], v[182:185], v[218:221], v[22:25]
	v_mfma_f32_16x16x32_bf16 v[6:9], v[162:165], v[222:225], 0
	v_mfma_f32_16x16x32_bf16 v[6:9], v[166:169], v[226:229], v[6:9]
	v_mfma_f32_16x16x32_bf16 v[2:5], v[170:173], v[222:225], 0
	v_mfma_f32_16x16x32_bf16 v[2:5], v[182:185], v[226:229], v[2:5]
	s_barrier
	s_setprio 0
	s_add_i32 s52, 0, 0x18000
	s_add_i32 s53, 0, 0x1c000
	v_add_u32_e32 v158, s52, v199
	v_add_u32_e32 v182, s53, v199
	ds_read_b128 v[134:137], v158
	ds_read_b128 v[150:153], v158 offset:1024
	ds_read_b128 v[154:157], v158 offset:2048
	ds_read_b128 v[158:161], v158 offset:3072
	ds_read_b128 v[162:165], v182
	ds_read_b128 v[166:169], v182 offset:1024
	ds_read_b128 v[170:173], v182 offset:2048
	ds_read_b128 v[182:185], v182 offset:3072
	s_add_u32 s34, s34, 0x40000
	s_addc_u32 s35, s35, 0
	s_mov_b32 m0, s41
	v_lshl_add_u64 v[234:235], s[34:35], 0, v[140:141]
	ds_read_b128 v[186:189], v201 offset:32768
	ds_read_b128 v[202:205], v201 offset:33792
	ds_read_b128 v[206:209], v201 offset:34816
	ds_read_b128 v[210:213], v201 offset:35840
	ds_read_b128 v[214:217], v201 offset:36864
	ds_read_b128 v[218:221], v201 offset:37888
	ds_read_b128 v[222:225], v201 offset:38912
	ds_read_b128 v[226:229], v201 offset:39936
	global_load_lds_dwordx4 v[234:235], off
	v_lshl_add_u64 v[234:235], s[34:35], 0, v[138:139]
	s_mov_b32 m0, s42
	s_nop 0
	global_load_lds_dwordx4 v[234:235], off
	s_waitcnt vmcnt(8)
	s_waitcnt lgkmcnt(0)
	s_setprio 1
	s_barrier
	v_mfma_f32_16x16x32_bf16 v[130:133], v[134:137], v[186:189], v[130:133]
	v_mfma_f32_16x16x32_bf16 v[130:133], v[150:153], v[202:205], v[130:133]
	v_mfma_f32_16x16x32_bf16 v[126:129], v[154:157], v[186:189], v[126:129]
	v_mfma_f32_16x16x32_bf16 v[126:129], v[158:161], v[202:205], v[126:129]
	v_mfma_f32_16x16x32_bf16 v[114:117], v[134:137], v[206:209], v[114:117]
	v_mfma_f32_16x16x32_bf16 v[114:117], v[150:153], v[210:213], v[114:117]
	v_mfma_f32_16x16x32_bf16 v[110:113], v[154:157], v[206:209], v[110:113]
	v_mfma_f32_16x16x32_bf16 v[110:113], v[158:161], v[210:213], v[110:113]
	v_mfma_f32_16x16x32_bf16 v[98:101], v[134:137], v[214:217], v[98:101]
	v_mfma_f32_16x16x32_bf16 v[98:101], v[150:153], v[218:221], v[98:101]
	v_mfma_f32_16x16x32_bf16 v[94:97], v[154:157], v[214:217], v[94:97]
	v_mfma_f32_16x16x32_bf16 v[94:97], v[158:161], v[218:221], v[94:97]
	v_mfma_f32_16x16x32_bf16 v[82:85], v[134:137], v[222:225], v[82:85]
	v_mfma_f32_16x16x32_bf16 v[82:85], v[150:153], v[226:229], v[82:85]
	v_mfma_f32_16x16x32_bf16 v[78:81], v[154:157], v[222:225], v[78:81]
	v_mfma_f32_16x16x32_bf16 v[78:81], v[158:161], v[226:229], v[78:81]
	v_mfma_f32_16x16x32_bf16 v[122:125], v[162:165], v[186:189], v[122:125]
	v_mfma_f32_16x16x32_bf16 v[122:125], v[166:169], v[202:205], v[122:125]
	v_mfma_f32_16x16x32_bf16 v[118:121], v[170:173], v[186:189], v[118:121]
	v_mfma_f32_16x16x32_bf16 v[118:121], v[182:185], v[202:205], v[118:121]
	v_mfma_f32_16x16x32_bf16 v[106:109], v[162:165], v[206:209], v[106:109]
	v_mfma_f32_16x16x32_bf16 v[106:109], v[166:169], v[210:213], v[106:109]
	v_mfma_f32_16x16x32_bf16 v[102:105], v[170:173], v[206:209], v[102:105]
	v_mfma_f32_16x16x32_bf16 v[102:105], v[182:185], v[210:213], v[102:105]
	v_mfma_f32_16x16x32_bf16 v[90:93], v[162:165], v[214:217], v[90:93]
	v_mfma_f32_16x16x32_bf16 v[90:93], v[166:169], v[218:221], v[90:93]
	v_mfma_f32_16x16x32_bf16 v[86:89], v[170:173], v[214:217], v[86:89]
	v_mfma_f32_16x16x32_bf16 v[86:89], v[182:185], v[218:221], v[86:89]
	v_mfma_f32_16x16x32_bf16 v[74:77], v[162:165], v[222:225], v[74:77]
	v_mfma_f32_16x16x32_bf16 v[74:77], v[166:169], v[226:229], v[74:77]
	v_mfma_f32_16x16x32_bf16 v[70:73], v[170:173], v[222:225], v[70:73]
	v_mfma_f32_16x16x32_bf16 v[70:73], v[182:185], v[226:229], v[70:73]
	s_barrier
	s_setprio 0
	s_add_i32 s34, s52, s36
	v_lshl_add_u64 v[174:175], v[174:175], 0, s[92:93]
	s_mov_b32 m0, s34
	ds_read_b128 v[186:189], v201 offset:49152
	ds_read_b128 v[202:205], v201 offset:50176
	ds_read_b128 v[206:209], v201 offset:51200
	ds_read_b128 v[210:213], v201 offset:52224
	ds_read_b128 v[214:217], v201 offset:53248
	ds_read_b128 v[218:221], v201 offset:54272
	ds_read_b128 v[222:225], v201 offset:55296
	ds_read_b128 v[226:229], v201 offset:56320
	global_load_lds_dwordx4 v[174:175], off
	s_add_i32 m0, s34, 0x2000
	s_add_u32 s30, s30, 0x40080
	v_lshl_add_u64 v[174:175], v[190:191], 0, s[92:93]
	s_addc_u32 s31, s31, 0
	s_add_i32 s34, s53, s36
	global_load_lds_dwordx4 v[174:175], off
	v_lshl_add_u64 v[174:175], s[30:31], 0, v[0:1]
	s_mov_b32 m0, s34
	s_nop 0
	global_load_lds_dwordx4 v[174:175], off
	v_lshl_add_u64 v[174:175], s[30:31], 0, v[14:15]
	s_add_i32 m0, s34, 0x2000
	s_nop 0
	global_load_lds_dwordx4 v[174:175], off
	v_lshl_add_u64 v[174:175], v[230:231], 0, s[92:93]
	s_mov_b32 m0, s43
	s_nop 0
	global_load_lds_dwordx4 v[174:175], off
	v_lshl_add_u64 v[174:175], v[232:233], 0, s[92:93]
	s_mov_b32 m0, s44
	s_nop 0
	global_load_lds_dwordx4 v[174:175], off
	s_waitcnt vmcnt(8)
	s_waitcnt lgkmcnt(0)
	s_setprio 1
	s_barrier
	v_mfma_f32_16x16x32_bf16 v[66:69], v[134:137], v[186:189], v[66:69]
	v_mfma_f32_16x16x32_bf16 v[66:69], v[150:153], v[202:205], v[66:69]
	v_mfma_f32_16x16x32_bf16 v[62:65], v[154:157], v[186:189], v[62:65]
	v_mfma_f32_16x16x32_bf16 v[62:65], v[158:161], v[202:205], v[62:65]
	v_mfma_f32_16x16x32_bf16 v[50:53], v[134:137], v[206:209], v[50:53]
	v_mfma_f32_16x16x32_bf16 v[50:53], v[150:153], v[210:213], v[50:53]
	v_mfma_f32_16x16x32_bf16 v[46:49], v[154:157], v[206:209], v[46:49]
	v_mfma_f32_16x16x32_bf16 v[46:49], v[158:161], v[210:213], v[46:49]
	v_mfma_f32_16x16x32_bf16 v[34:37], v[134:137], v[214:217], v[34:37]
	v_mfma_f32_16x16x32_bf16 v[34:37], v[150:153], v[218:221], v[34:37]
	v_mfma_f32_16x16x32_bf16 v[30:33], v[154:157], v[214:217], v[30:33]
	v_mfma_f32_16x16x32_bf16 v[30:33], v[158:161], v[218:221], v[30:33]
	v_mfma_f32_16x16x32_bf16 v[18:21], v[134:137], v[222:225], v[18:21]
	v_mfma_f32_16x16x32_bf16 v[18:21], v[150:153], v[226:229], v[18:21]
	v_mfma_f32_16x16x32_bf16 v[10:13], v[154:157], v[222:225], v[10:13]
	v_mfma_f32_16x16x32_bf16 v[10:13], v[158:161], v[226:229], v[10:13]
	v_mfma_f32_16x16x32_bf16 v[58:61], v[162:165], v[186:189], v[58:61]
	v_mfma_f32_16x16x32_bf16 v[58:61], v[166:169], v[202:205], v[58:61]
	v_mfma_f32_16x16x32_bf16 v[54:57], v[170:173], v[186:189], v[54:57]
	v_mfma_f32_16x16x32_bf16 v[54:57], v[182:185], v[202:205], v[54:57]
	v_mfma_f32_16x16x32_bf16 v[42:45], v[162:165], v[206:209], v[42:45]
	v_mfma_f32_16x16x32_bf16 v[42:45], v[166:169], v[210:213], v[42:45]
	v_mfma_f32_16x16x32_bf16 v[38:41], v[170:173], v[206:209], v[38:41]
	v_mfma_f32_16x16x32_bf16 v[38:41], v[182:185], v[210:213], v[38:41]
	v_mfma_f32_16x16x32_bf16 v[26:29], v[162:165], v[214:217], v[26:29]
	v_mfma_f32_16x16x32_bf16 v[26:29], v[166:169], v[218:221], v[26:29]
	v_mfma_f32_16x16x32_bf16 v[22:25], v[170:173], v[214:217], v[22:25]
	v_mfma_f32_16x16x32_bf16 v[22:25], v[182:185], v[218:221], v[22:25]
	v_mfma_f32_16x16x32_bf16 v[6:9], v[162:165], v[222:225], v[6:9]
	v_mfma_f32_16x16x32_bf16 v[6:9], v[166:169], v[226:229], v[6:9]
	v_mfma_f32_16x16x32_bf16 v[2:5], v[170:173], v[222:225], v[2:5]
	v_mfma_f32_16x16x32_bf16 v[2:5], v[182:185], v[226:229], v[2:5]
	s_barrier
	s_setprio 0
	s_add_i32 s51, s51, 2
	s_add_u32 s0, s0, 0x100
	s_addc_u32 s1, s1, 0
	s_add_u32 s49, s49, 0x100
	s_addc_u32 s50, s50, 0
	s_cmp_gt_u32 s51, 13
	s_cbranch_scc1 .Lpeel_exit_1
.LBB0_566:
	s_add_u32 s30, s0, 0xfffc0080
	s_addc_u32 s31, s1, -1
	s_add_i32 s52, 0, 0x10000
	s_cmp_eq_u32 s51, 12
	s_cselect_b32 s35, s3, s31
	s_cselect_b32 s34, s25, s30
	s_cselect_b32 s31, s23, s50
	s_cselect_b32 s30, s48, s49
	s_add_i32 s54, 0, 0x14000
	v_add_u32_e32 v158, s52, v199
	v_add_u32_e32 v174, s54, v199
	ds_read_b128 v[134:137], v158
	ds_read_b128 v[150:153], v158 offset:1024
	ds_read_b128 v[154:157], v158 offset:2048
	ds_read_b128 v[158:161], v158 offset:3072
	ds_read_b128 v[162:165], v174
	ds_read_b128 v[166:169], v174 offset:1024
	ds_read_b128 v[170:173], v174 offset:2048
	ds_read_b128 v[182:185], v174 offset:3072
	v_lshl_add_u64 v[174:175], s[0:1], 0, v[146:147]
	s_add_i32 m0, s39, 0xc000
	ds_read_b128 v[186:189], v201
	ds_read_b128 v[202:205], v201 offset:1024
	ds_read_b128 v[206:209], v201 offset:2048
	ds_read_b128 v[210:213], v201 offset:3072
	ds_read_b128 v[214:217], v201 offset:4096
	ds_read_b128 v[218:221], v201 offset:5120
	ds_read_b128 v[222:225], v201 offset:6144
	ds_read_b128 v[226:229], v201 offset:7168
	global_load_lds_dwordx4 v[174:175], off
	v_lshl_add_u64 v[174:175], s[0:1], 0, v[148:149]
	s_add_i32 m0, s39, 0xe000
	s_nop 0
	global_load_lds_dwordx4 v[174:175], off
	s_waitcnt vmcnt(8)
	s_waitcnt lgkmcnt(0)
	s_setprio 1
	s_barrier
	v_mfma_f32_16x16x32_bf16 v[130:133], v[134:137], v[186:189], v[130:133]
	v_mfma_f32_16x16x32_bf16 v[130:133], v[150:153], v[202:205], v[130:133]
	v_mfma_f32_16x16x32_bf16 v[126:129], v[154:157], v[186:189], v[126:129]
	v_mfma_f32_16x16x32_bf16 v[126:129], v[158:161], v[202:205], v[126:129]
	v_mfma_f32_16x16x32_bf16 v[114:117], v[134:137], v[206:209], v[114:117]
	v_mfma_f32_16x16x32_bf16 v[114:117], v[150:153], v[210:213], v[114:117]
	v_mfma_f32_16x16x32_bf16 v[110:113], v[154:157], v[206:209], v[110:113]
	v_mfma_f32_16x16x32_bf16 v[110:113], v[158:161], v[210:213], v[110:113]
	v_mfma_f32_16x16x32_bf16 v[98:101], v[134:137], v[214:217], v[98:101]
	v_mfma_f32_16x16x32_bf16 v[98:101], v[150:153], v[218:221], v[98:101]
	v_mfma_f32_16x16x32_bf16 v[94:97], v[154:157], v[214:217], v[94:97]
	v_mfma_f32_16x16x32_bf16 v[94:97], v[158:161], v[218:221], v[94:97]
	v_mfma_f32_16x16x32_bf16 v[82:85], v[134:137], v[222:225], v[82:85]
	v_mfma_f32_16x16x32_bf16 v[82:85], v[150:153], v[226:229], v[82:85]
	v_mfma_f32_16x16x32_bf16 v[78:81], v[154:157], v[222:225], v[78:81]
	v_mfma_f32_16x16x32_bf16 v[78:81], v[158:161], v[226:229], v[78:81]
	v_mfma_f32_16x16x32_bf16 v[122:125], v[162:165], v[186:189], v[122:125]
	v_mfma_f32_16x16x32_bf16 v[122:125], v[166:169], v[202:205], v[122:125]
	v_mfma_f32_16x16x32_bf16 v[118:121], v[170:173], v[186:189], v[118:121]
	v_mfma_f32_16x16x32_bf16 v[118:121], v[182:185], v[202:205], v[118:121]
	v_mfma_f32_16x16x32_bf16 v[106:109], v[162:165], v[206:209], v[106:109]
	v_mfma_f32_16x16x32_bf16 v[106:109], v[166:169], v[210:213], v[106:109]
	v_mfma_f32_16x16x32_bf16 v[102:105], v[170:173], v[206:209], v[102:105]
	v_mfma_f32_16x16x32_bf16 v[102:105], v[182:185], v[210:213], v[102:105]
	v_mfma_f32_16x16x32_bf16 v[90:93], v[162:165], v[214:217], v[90:93]
	v_mfma_f32_16x16x32_bf16 v[90:93], v[166:169], v[218:221], v[90:93]
	v_mfma_f32_16x16x32_bf16 v[86:89], v[170:173], v[214:217], v[86:89]
	v_mfma_f32_16x16x32_bf16 v[86:89], v[182:185], v[218:221], v[86:89]
	v_mfma_f32_16x16x32_bf16 v[74:77], v[162:165], v[222:225], v[74:77]
	v_mfma_f32_16x16x32_bf16 v[74:77], v[166:169], v[226:229], v[74:77]
	v_mfma_f32_16x16x32_bf16 v[70:73], v[170:173], v[222:225], v[70:73]
	v_mfma_f32_16x16x32_bf16 v[70:73], v[182:185], v[226:229], v[70:73]
	s_barrier
	s_setprio 0
	s_add_i32 s52, s52, s36
	v_lshl_add_u64 v[174:175], s[30:31], 0, v[0:1]
	s_mov_b32 m0, s52
	ds_read_b128 v[186:189], v201 offset:16384
	ds_read_b128 v[202:205], v201 offset:17408
	ds_read_b128 v[206:209], v201 offset:18432
	ds_read_b128 v[210:213], v201 offset:19456
	ds_read_b128 v[214:217], v201 offset:20480
	ds_read_b128 v[218:221], v201 offset:21504
	ds_read_b128 v[222:225], v201 offset:22528
	ds_read_b128 v[226:229], v201 offset:23552
	global_load_lds_dwordx4 v[174:175], off
	s_add_i32 m0, s52, 0x2000
	s_add_u32 s52, s30, 0x40000
	v_lshl_add_u64 v[190:191], s[30:31], 0, v[14:15]
	s_addc_u32 s53, s31, 0
	s_add_i32 s54, s54, s36
	global_load_lds_dwordx4 v[190:191], off
	v_lshl_add_u64 v[230:231], s[52:53], 0, v[0:1]
	s_mov_b32 m0, s54
	v_lshl_add_u64 v[232:233], s[34:35], 0, v[138:139]
	global_load_lds_dwordx4 v[230:231], off
	v_lshl_add_u64 v[230:231], s[52:53], 0, v[14:15]
	s_add_i32 m0, s54, 0x2000
	s_nop 0
	global_load_lds_dwordx4 v[230:231], off
	v_lshl_add_u64 v[230:231], s[34:35], 0, v[140:141]
	s_mov_b32 m0, s39
	s_nop 0
	global_load_lds_dwordx4 v[230:231], off
	s_mov_b32 m0, s40
	s_nop 0
	global_load_lds_dwordx4 v[232:233], off
	s_waitcnt vmcnt(8)
	s_waitcnt lgkmcnt(0)
	s_setprio 1
	s_barrier
	v_mfma_f32_16x16x32_bf16 v[66:69], v[134:137], v[186:189], v[66:69]
	v_mfma_f32_16x16x32_bf16 v[66:69], v[150:153], v[202:205], v[66:69]
	v_mfma_f32_16x16x32_bf16 v[62:65], v[154:157], v[186:189], v[62:65]
	v_mfma_f32_16x16x32_bf16 v[62:65], v[158:161], v[202:205], v[62:65]
	v_mfma_f32_16x16x32_bf16 v[50:53], v[134:137], v[206:209], v[50:53]
	v_mfma_f32_16x16x32_bf16 v[50:53], v[150:153], v[210:213], v[50:53]
	v_mfma_f32_16x16x32_bf16 v[46:49], v[154:157], v[206:209], v[46:49]
	v_mfma_f32_16x16x32_bf16 v[46:49], v[158:161], v[210:213], v[46:49]
	v_mfma_f32_16x16x32_bf16 v[34:37], v[134:137], v[214:217], v[34:37]
	v_mfma_f32_16x16x32_bf16 v[34:37], v[150:153], v[218:221], v[34:37]
	v_mfma_f32_16x16x32_bf16 v[30:33], v[154:157], v[214:217], v[30:33]
	v_mfma_f32_16x16x32_bf16 v[30:33], v[158:161], v[218:221], v[30:33]
	v_mfma_f32_16x16x32_bf16 v[18:21], v[134:137], v[222:225], v[18:21]
	v_mfma_f32_16x16x32_bf16 v[18:21], v[150:153], v[226:229], v[18:21]
	v_mfma_f32_16x16x32_bf16 v[10:13], v[154:157], v[222:225], v[10:13]
	v_mfma_f32_16x16x32_bf16 v[10:13], v[158:161], v[226:229], v[10:13]
	v_mfma_f32_16x16x32_bf16 v[58:61], v[162:165], v[186:189], v[58:61]
	v_mfma_f32_16x16x32_bf16 v[58:61], v[166:169], v[202:205], v[58:61]
	v_mfma_f32_16x16x32_bf16 v[54:57], v[170:173], v[186:189], v[54:57]
	v_mfma_f32_16x16x32_bf16 v[54:57], v[182:185], v[202:205], v[54:57]
	v_mfma_f32_16x16x32_bf16 v[42:45], v[162:165], v[206:209], v[42:45]
	v_mfma_f32_16x16x32_bf16 v[42:45], v[166:169], v[210:213], v[42:45]
	v_mfma_f32_16x16x32_bf16 v[38:41], v[170:173], v[206:209], v[38:41]
	v_mfma_f32_16x16x32_bf16 v[38:41], v[182:185], v[210:213], v[38:41]
	v_mfma_f32_16x16x32_bf16 v[26:29], v[162:165], v[214:217], v[26:29]
	v_mfma_f32_16x16x32_bf16 v[26:29], v[166:169], v[218:221], v[26:29]
	v_mfma_f32_16x16x32_bf16 v[22:25], v[170:173], v[214:217], v[22:25]
	v_mfma_f32_16x16x32_bf16 v[22:25], v[182:185], v[218:221], v[22:25]
	v_mfma_f32_16x16x32_bf16 v[6:9], v[162:165], v[222:225], v[6:9]
	v_mfma_f32_16x16x32_bf16 v[6:9], v[166:169], v[226:229], v[6:9]
	v_mfma_f32_16x16x32_bf16 v[2:5], v[170:173], v[222:225], v[2:5]
	v_mfma_f32_16x16x32_bf16 v[2:5], v[182:185], v[226:229], v[2:5]
	s_barrier
	s_setprio 0
	s_add_i32 s52, 0, 0x18000
	s_add_i32 s53, 0, 0x1c000
	v_add_u32_e32 v158, s52, v199
	v_add_u32_e32 v182, s53, v199
	ds_read_b128 v[134:137], v158
	ds_read_b128 v[150:153], v158 offset:1024
	ds_read_b128 v[154:157], v158 offset:2048
	ds_read_b128 v[158:161], v158 offset:3072
	ds_read_b128 v[162:165], v182
	ds_read_b128 v[166:169], v182 offset:1024
	ds_read_b128 v[170:173], v182 offset:2048
	ds_read_b128 v[182:185], v182 offset:3072
	s_add_u32 s34, s34, 0x40000
	s_addc_u32 s35, s35, 0
	s_mov_b32 m0, s41
	v_lshl_add_u64 v[234:235], s[34:35], 0, v[140:141]
	ds_read_b128 v[186:189], v201 offset:32768
	ds_read_b128 v[202:205], v201 offset:33792
	ds_read_b128 v[206:209], v201 offset:34816
	ds_read_b128 v[210:213], v201 offset:35840
	ds_read_b128 v[214:217], v201 offset:36864
	ds_read_b128 v[218:221], v201 offset:37888
	ds_read_b128 v[222:225], v201 offset:38912
	ds_read_b128 v[226:229], v201 offset:39936
	global_load_lds_dwordx4 v[234:235], off
	v_lshl_add_u64 v[234:235], s[34:35], 0, v[138:139]
	s_mov_b32 m0, s42
	s_nop 0
	global_load_lds_dwordx4 v[234:235], off
	s_waitcnt vmcnt(8)
	s_waitcnt lgkmcnt(0)
	s_setprio 1
	s_barrier
	v_mfma_f32_16x16x32_bf16 v[130:133], v[134:137], v[186:189], v[130:133]
	v_mfma_f32_16x16x32_bf16 v[130:133], v[150:153], v[202:205], v[130:133]
	v_mfma_f32_16x16x32_bf16 v[126:129], v[154:157], v[186:189], v[126:129]
	v_mfma_f32_16x16x32_bf16 v[126:129], v[158:161], v[202:205], v[126:129]
	v_mfma_f32_16x16x32_bf16 v[114:117], v[134:137], v[206:209], v[114:117]
	v_mfma_f32_16x16x32_bf16 v[114:117], v[150:153], v[210:213], v[114:117]
	v_mfma_f32_16x16x32_bf16 v[110:113], v[154:157], v[206:209], v[110:113]
	v_mfma_f32_16x16x32_bf16 v[110:113], v[158:161], v[210:213], v[110:113]
	v_mfma_f32_16x16x32_bf16 v[98:101], v[134:137], v[214:217], v[98:101]
	v_mfma_f32_16x16x32_bf16 v[98:101], v[150:153], v[218:221], v[98:101]
	v_mfma_f32_16x16x32_bf16 v[94:97], v[154:157], v[214:217], v[94:97]
	v_mfma_f32_16x16x32_bf16 v[94:97], v[158:161], v[218:221], v[94:97]
	v_mfma_f32_16x16x32_bf16 v[82:85], v[134:137], v[222:225], v[82:85]
	v_mfma_f32_16x16x32_bf16 v[82:85], v[150:153], v[226:229], v[82:85]
	v_mfma_f32_16x16x32_bf16 v[78:81], v[154:157], v[222:225], v[78:81]
	v_mfma_f32_16x16x32_bf16 v[78:81], v[158:161], v[226:229], v[78:81]
	v_mfma_f32_16x16x32_bf16 v[122:125], v[162:165], v[186:189], v[122:125]
	v_mfma_f32_16x16x32_bf16 v[122:125], v[166:169], v[202:205], v[122:125]
	v_mfma_f32_16x16x32_bf16 v[118:121], v[170:173], v[186:189], v[118:121]
	v_mfma_f32_16x16x32_bf16 v[118:121], v[182:185], v[202:205], v[118:121]
	v_mfma_f32_16x16x32_bf16 v[106:109], v[162:165], v[206:209], v[106:109]
	v_mfma_f32_16x16x32_bf16 v[106:109], v[166:169], v[210:213], v[106:109]
	v_mfma_f32_16x16x32_bf16 v[102:105], v[170:173], v[206:209], v[102:105]
	v_mfma_f32_16x16x32_bf16 v[102:105], v[182:185], v[210:213], v[102:105]
	v_mfma_f32_16x16x32_bf16 v[90:93], v[162:165], v[214:217], v[90:93]
	v_mfma_f32_16x16x32_bf16 v[90:93], v[166:169], v[218:221], v[90:93]
	v_mfma_f32_16x16x32_bf16 v[86:89], v[170:173], v[214:217], v[86:89]
	v_mfma_f32_16x16x32_bf16 v[86:89], v[182:185], v[218:221], v[86:89]
	v_mfma_f32_16x16x32_bf16 v[74:77], v[162:165], v[222:225], v[74:77]
	v_mfma_f32_16x16x32_bf16 v[74:77], v[166:169], v[226:229], v[74:77]
	v_mfma_f32_16x16x32_bf16 v[70:73], v[170:173], v[222:225], v[70:73]
	v_mfma_f32_16x16x32_bf16 v[70:73], v[182:185], v[226:229], v[70:73]
	s_barrier
	s_setprio 0
	s_add_i32 s34, s52, s36
	v_lshl_add_u64 v[174:175], v[174:175], 0, s[92:93]
	s_mov_b32 m0, s34
	ds_read_b128 v[186:189], v201 offset:49152
	ds_read_b128 v[202:205], v201 offset:50176
	ds_read_b128 v[206:209], v201 offset:51200
	ds_read_b128 v[210:213], v201 offset:52224
	ds_read_b128 v[214:217], v201 offset:53248
	ds_read_b128 v[218:221], v201 offset:54272
	ds_read_b128 v[222:225], v201 offset:55296
	ds_read_b128 v[226:229], v201 offset:56320
	global_load_lds_dwordx4 v[174:175], off
	s_add_i32 m0, s34, 0x2000
	s_add_u32 s30, s30, 0x40080
	v_lshl_add_u64 v[174:175], v[190:191], 0, s[92:93]
	s_addc_u32 s31, s31, 0
	s_add_i32 s34, s53, s36
	global_load_lds_dwordx4 v[174:175], off
	v_lshl_add_u64 v[174:175], s[30:31], 0, v[0:1]
	s_mov_b32 m0, s34
	s_nop 0
	global_load_lds_dwordx4 v[174:175], off
	v_lshl_add_u64 v[174:175], s[30:31], 0, v[14:15]
	s_add_i32 m0, s34, 0x2000
	s_nop 0
	global_load_lds_dwordx4 v[174:175], off
	v_lshl_add_u64 v[174:175], v[230:231], 0, s[92:93]
	s_mov_b32 m0, s43
	s_nop 0
	global_load_lds_dwordx4 v[174:175], off
	v_lshl_add_u64 v[174:175], v[232:233], 0, s[92:93]
	s_mov_b32 m0, s44
	s_nop 0
	global_load_lds_dwordx4 v[174:175], off
	s_waitcnt vmcnt(8)
	s_waitcnt lgkmcnt(0)
	s_setprio 1
	s_barrier
	v_mfma_f32_16x16x32_bf16 v[66:69], v[134:137], v[186:189], v[66:69]
	v_mfma_f32_16x16x32_bf16 v[66:69], v[150:153], v[202:205], v[66:69]
	v_mfma_f32_16x16x32_bf16 v[62:65], v[154:157], v[186:189], v[62:65]
	v_mfma_f32_16x16x32_bf16 v[62:65], v[158:161], v[202:205], v[62:65]
	v_mfma_f32_16x16x32_bf16 v[50:53], v[134:137], v[206:209], v[50:53]
	v_mfma_f32_16x16x32_bf16 v[50:53], v[150:153], v[210:213], v[50:53]
	v_mfma_f32_16x16x32_bf16 v[46:49], v[154:157], v[206:209], v[46:49]
	v_mfma_f32_16x16x32_bf16 v[46:49], v[158:161], v[210:213], v[46:49]
	v_mfma_f32_16x16x32_bf16 v[34:37], v[134:137], v[214:217], v[34:37]
	v_mfma_f32_16x16x32_bf16 v[34:37], v[150:153], v[218:221], v[34:37]
	v_mfma_f32_16x16x32_bf16 v[30:33], v[154:157], v[214:217], v[30:33]
	v_mfma_f32_16x16x32_bf16 v[30:33], v[158:161], v[218:221], v[30:33]
	v_mfma_f32_16x16x32_bf16 v[18:21], v[134:137], v[222:225], v[18:21]
	v_mfma_f32_16x16x32_bf16 v[18:21], v[150:153], v[226:229], v[18:21]
	v_mfma_f32_16x16x32_bf16 v[10:13], v[154:157], v[222:225], v[10:13]
	v_mfma_f32_16x16x32_bf16 v[10:13], v[158:161], v[226:229], v[10:13]
	v_mfma_f32_16x16x32_bf16 v[58:61], v[162:165], v[186:189], v[58:61]
	v_mfma_f32_16x16x32_bf16 v[58:61], v[166:169], v[202:205], v[58:61]
	v_mfma_f32_16x16x32_bf16 v[54:57], v[170:173], v[186:189], v[54:57]
	v_mfma_f32_16x16x32_bf16 v[54:57], v[182:185], v[202:205], v[54:57]
	v_mfma_f32_16x16x32_bf16 v[42:45], v[162:165], v[206:209], v[42:45]
	v_mfma_f32_16x16x32_bf16 v[42:45], v[166:169], v[210:213], v[42:45]
	v_mfma_f32_16x16x32_bf16 v[38:41], v[170:173], v[206:209], v[38:41]
	v_mfma_f32_16x16x32_bf16 v[38:41], v[182:185], v[210:213], v[38:41]
	v_mfma_f32_16x16x32_bf16 v[26:29], v[162:165], v[214:217], v[26:29]
	v_mfma_f32_16x16x32_bf16 v[26:29], v[166:169], v[218:221], v[26:29]
	v_mfma_f32_16x16x32_bf16 v[22:25], v[170:173], v[214:217], v[22:25]
	v_mfma_f32_16x16x32_bf16 v[22:25], v[182:185], v[218:221], v[22:25]
	v_mfma_f32_16x16x32_bf16 v[6:9], v[162:165], v[222:225], v[6:9]
	v_mfma_f32_16x16x32_bf16 v[6:9], v[166:169], v[226:229], v[6:9]
	v_mfma_f32_16x16x32_bf16 v[2:5], v[170:173], v[222:225], v[2:5]
	v_mfma_f32_16x16x32_bf16 v[2:5], v[182:185], v[226:229], v[2:5]
	s_barrier
	s_setprio 0
	s_add_i32 s51, s51, 2
	s_add_u32 s0, s0, 0x100
	s_addc_u32 s1, s1, 0
	s_add_u32 s49, s49, 0x100
	s_addc_u32 s50, s50, 0
	s_cmp_gt_u32 s51, 13
	s_cbranch_scc0 .LBB0_566

.LBB0_636:
	s_add_u32 s22, s22, 0x80
	s_addc_u32 s23, s23, 0
	s_add_u32 s45, s24, 0x100
	s_addc_u32 s46, s25, 0
	s_mov_b32 s24, 0
	s_add_i32 s47, s24, 2
	s_add_u32 s48, s22, 0x80
	s_addc_u32 s25, s23, 0
	s_add_i32 s50, 0, 0x10000
	s_cmp_eq_u32 s40, s24
	s_cselect_b32 s25, s7, s25
	s_cselect_b32 s24, s6, s48
	v_add_u32_e32 v135, s50, v249
	s_cselect_b32 s49, s21, s46
	s_cselect_b32 s48, s20, s45
	s_add_i32 s51, 0, 0x14000
	ds_read_b128 v[142:145], v135
	ds_read_b128 v[146:149], v135 offset:1024
	ds_read_b128 v[150:153], v135 offset:2048
	ds_read_b128 v[154:157], v135 offset:3072
	v_add_u32_e32 v135, s51, v249
	ds_read_b128 v[158:161], v135
	ds_read_b128 v[162:165], v135 offset:1024
	ds_read_b128 v[166:169], v135 offset:2048
	ds_read_b128 v[170:173], v135 offset:3072
	v_lshl_add_u64 v[174:175], s[22:23], 0, v[138:139]
	s_add_i32 m0, s31, 0xc000
	ds_read_b128 v[182:185], v251
	ds_read_b128 v[186:189], v251 offset:1024
	ds_read_b128 v[190:193], v251 offset:2048
	ds_read_b128 v[194:197], v251 offset:3072
	ds_read_b128 v[198:201], v251 offset:4096
	ds_read_b128 v[202:205], v251 offset:5120
	ds_read_b128 v[206:209], v251 offset:6144
	ds_read_b128 v[210:213], v251 offset:7168
	global_load_lds_dwordx4 v[174:175], off
	v_lshl_add_u64 v[174:175], s[22:23], 0, v[140:141]
	s_add_i32 m0, s31, 0xe000
	s_nop 0
	global_load_lds_dwordx4 v[174:175], off
	s_waitcnt vmcnt(8)
	s_waitcnt lgkmcnt(0)
	s_setprio 1
	s_barrier
	v_mfma_f32_16x16x32_bf16 v[130:133], v[142:145], v[182:185], 0
	v_mfma_f32_16x16x32_bf16 v[130:133], v[146:149], v[186:189], v[130:133]
	v_mfma_f32_16x16x32_bf16 v[126:129], v[150:153], v[182:185], 0
	v_mfma_f32_16x16x32_bf16 v[126:129], v[154:157], v[186:189], v[126:129]
	v_mfma_f32_16x16x32_bf16 v[114:117], v[142:145], v[190:193], 0
	v_mfma_f32_16x16x32_bf16 v[114:117], v[146:149], v[194:197], v[114:117]
	v_mfma_f32_16x16x32_bf16 v[110:113], v[150:153], v[190:193], 0
	v_mfma_f32_16x16x32_bf16 v[110:113], v[154:157], v[194:197], v[110:113]
	v_mfma_f32_16x16x32_bf16 v[98:101], v[142:145], v[198:201], 0
	v_mfma_f32_16x16x32_bf16 v[98:101], v[146:149], v[202:205], v[98:101]
	v_mfma_f32_16x16x32_bf16 v[94:97], v[150:153], v[198:201], 0
	v_mfma_f32_16x16x32_bf16 v[94:97], v[154:157], v[202:205], v[94:97]
	v_mfma_f32_16x16x32_bf16 v[82:85], v[142:145], v[206:209], 0
	v_mfma_f32_16x16x32_bf16 v[82:85], v[146:149], v[210:213], v[82:85]
	v_mfma_f32_16x16x32_bf16 v[78:81], v[150:153], v[206:209], 0
	v_mfma_f32_16x16x32_bf16 v[78:81], v[154:157], v[210:213], v[78:81]
	v_mfma_f32_16x16x32_bf16 v[122:125], v[158:161], v[182:185], 0
	v_mfma_f32_16x16x32_bf16 v[122:125], v[162:165], v[186:189], v[122:125]
	v_mfma_f32_16x16x32_bf16 v[118:121], v[166:169], v[182:185], 0
	v_mfma_f32_16x16x32_bf16 v[118:121], v[170:173], v[186:189], v[118:121]
	v_mfma_f32_16x16x32_bf16 v[106:109], v[158:161], v[190:193], 0
	v_mfma_f32_16x16x32_bf16 v[106:109], v[162:165], v[194:197], v[106:109]
	v_mfma_f32_16x16x32_bf16 v[102:105], v[166:169], v[190:193], 0
	v_mfma_f32_16x16x32_bf16 v[102:105], v[170:173], v[194:197], v[102:105]
	v_mfma_f32_16x16x32_bf16 v[90:93], v[158:161], v[198:201], 0
	v_mfma_f32_16x16x32_bf16 v[90:93], v[162:165], v[202:205], v[90:93]
	v_mfma_f32_16x16x32_bf16 v[86:89], v[166:169], v[198:201], 0
	v_mfma_f32_16x16x32_bf16 v[86:89], v[170:173], v[202:205], v[86:89]
	v_mfma_f32_16x16x32_bf16 v[74:77], v[158:161], v[206:209], 0
	v_mfma_f32_16x16x32_bf16 v[74:77], v[162:165], v[210:213], v[74:77]
	v_mfma_f32_16x16x32_bf16 v[70:73], v[166:169], v[206:209], 0
	v_mfma_f32_16x16x32_bf16 v[70:73], v[170:173], v[210:213], v[70:73]
	s_barrier
	s_setprio 0
	s_add_i32 s50, s50, s30
	v_lshl_add_u64 v[174:175], s[48:49], 0, v[0:1]
	s_mov_b32 m0, s50
	ds_read_b128 v[182:185], v251 offset:16384
	ds_read_b128 v[186:189], v251 offset:17408
	ds_read_b128 v[190:193], v251 offset:18432
	ds_read_b128 v[194:197], v251 offset:19456
	ds_read_b128 v[198:201], v251 offset:20480
	ds_read_b128 v[202:205], v251 offset:21504
	ds_read_b128 v[206:209], v251 offset:22528
	ds_read_b128 v[210:213], v251 offset:23552
	global_load_lds_dwordx4 v[174:175], off
	s_add_i32 m0, s50, 0x2000
	v_lshl_add_u64 v[214:215], s[48:49], 0, v[14:15]
	s_add_u32 s48, s48, s10
	s_addc_u32 s49, s49, 0
	s_add_i32 s50, s51, s30
	global_load_lds_dwordx4 v[214:215], off
	v_lshl_add_u64 v[216:217], s[48:49], 0, v[0:1]
	s_mov_b32 m0, s50
	v_lshl_add_u64 v[218:219], s[48:49], 0, v[14:15]
	global_load_lds_dwordx4 v[216:217], off
	s_add_i32 m0, s50, 0x2000
	v_lshl_add_u64 v[220:221], s[24:25], 0, v[0:1]
	global_load_lds_dwordx4 v[218:219], off
	s_mov_b32 m0, s31
	v_lshl_add_u64 v[222:223], s[24:25], 0, v[14:15]
	global_load_lds_dwordx4 v[220:221], off
	s_mov_b32 m0, s34
	s_nop 0
	global_load_lds_dwordx4 v[222:223], off
	s_waitcnt vmcnt(8)
	s_waitcnt lgkmcnt(0)
	s_setprio 1
	s_barrier
	v_mfma_f32_16x16x32_bf16 v[66:69], v[142:145], v[182:185], 0
	v_mfma_f32_16x16x32_bf16 v[66:69], v[146:149], v[186:189], v[66:69]
	v_mfma_f32_16x16x32_bf16 v[62:65], v[150:153], v[182:185], 0
	v_mfma_f32_16x16x32_bf16 v[62:65], v[154:157], v[186:189], v[62:65]
	v_mfma_f32_16x16x32_bf16 v[50:53], v[142:145], v[190:193], 0
	v_mfma_f32_16x16x32_bf16 v[50:53], v[146:149], v[194:197], v[50:53]
	v_mfma_f32_16x16x32_bf16 v[46:49], v[150:153], v[190:193], 0
	v_mfma_f32_16x16x32_bf16 v[46:49], v[154:157], v[194:197], v[46:49]
	v_mfma_f32_16x16x32_bf16 v[34:37], v[142:145], v[198:201], 0
	v_mfma_f32_16x16x32_bf16 v[34:37], v[146:149], v[202:205], v[34:37]
	v_mfma_f32_16x16x32_bf16 v[30:33], v[150:153], v[198:201], 0
	v_mfma_f32_16x16x32_bf16 v[30:33], v[154:157], v[202:205], v[30:33]
	v_mfma_f32_16x16x32_bf16 v[18:21], v[142:145], v[206:209], 0
	v_mfma_f32_16x16x32_bf16 v[18:21], v[146:149], v[210:213], v[18:21]
	v_mfma_f32_16x16x32_bf16 v[10:13], v[150:153], v[206:209], 0
	v_mfma_f32_16x16x32_bf16 v[10:13], v[154:157], v[210:213], v[10:13]
	v_mfma_f32_16x16x32_bf16 v[58:61], v[158:161], v[182:185], 0
	v_mfma_f32_16x16x32_bf16 v[58:61], v[162:165], v[186:189], v[58:61]
	v_mfma_f32_16x16x32_bf16 v[54:57], v[166:169], v[182:185], 0
	v_mfma_f32_16x16x32_bf16 v[54:57], v[170:173], v[186:189], v[54:57]
	v_mfma_f32_16x16x32_bf16 v[42:45], v[158:161], v[190:193], 0
	v_mfma_f32_16x16x32_bf16 v[42:45], v[162:165], v[194:197], v[42:45]
	v_mfma_f32_16x16x32_bf16 v[38:41], v[166:169], v[190:193], 0
	v_mfma_f32_16x16x32_bf16 v[38:41], v[170:173], v[194:197], v[38:41]
	v_mfma_f32_16x16x32_bf16 v[26:29], v[158:161], v[198:201], 0
	v_mfma_f32_16x16x32_bf16 v[26:29], v[162:165], v[202:205], v[26:29]
	v_mfma_f32_16x16x32_bf16 v[22:25], v[166:169], v[198:201], 0
	v_mfma_f32_16x16x32_bf16 v[22:25], v[170:173], v[202:205], v[22:25]
	v_mfma_f32_16x16x32_bf16 v[6:9], v[158:161], v[206:209], 0
	v_mfma_f32_16x16x32_bf16 v[6:9], v[162:165], v[210:213], v[6:9]
	v_mfma_f32_16x16x32_bf16 v[2:5], v[166:169], v[206:209], 0
	v_mfma_f32_16x16x32_bf16 v[2:5], v[170:173], v[210:213], v[2:5]
	s_barrier
	s_setprio 0
	s_add_i32 s48, 0, 0x18000
	v_add_u32_e32 v135, s48, v249
	s_add_i32 s49, 0, 0x1c000
	ds_read_b128 v[142:145], v135
	ds_read_b128 v[146:149], v135 offset:1024
	ds_read_b128 v[150:153], v135 offset:2048
	ds_read_b128 v[154:157], v135 offset:3072
	v_add_u32_e32 v135, s49, v249
	ds_read_b128 v[158:161], v135
	ds_read_b128 v[162:165], v135 offset:1024
	ds_read_b128 v[166:169], v135 offset:2048
	ds_read_b128 v[170:173], v135 offset:3072
	s_add_u32 s24, s24, s10
	s_addc_u32 s25, s25, 0
	s_mov_b32 m0, s35
	v_lshl_add_u64 v[224:225], s[24:25], 0, v[0:1]
	ds_read_b128 v[182:185], v251 offset:32768
	ds_read_b128 v[186:189], v251 offset:33792
	ds_read_b128 v[190:193], v251 offset:34816
	ds_read_b128 v[194:197], v251 offset:35840
	ds_read_b128 v[198:201], v251 offset:36864
	ds_read_b128 v[202:205], v251 offset:37888
	ds_read_b128 v[206:209], v251 offset:38912
	ds_read_b128 v[210:213], v251 offset:39936
	global_load_lds_dwordx4 v[224:225], off
	v_lshl_add_u64 v[224:225], s[24:25], 0, v[14:15]
	s_mov_b32 m0, s36
	s_nop 0
	global_load_lds_dwordx4 v[224:225], off
	s_waitcnt vmcnt(8)
	s_waitcnt lgkmcnt(0)
	s_setprio 1
	s_barrier
	v_mfma_f32_16x16x32_bf16 v[130:133], v[142:145], v[182:185], v[130:133]
	v_mfma_f32_16x16x32_bf16 v[130:133], v[146:149], v[186:189], v[130:133]
	v_mfma_f32_16x16x32_bf16 v[126:129], v[150:153], v[182:185], v[126:129]
	v_mfma_f32_16x16x32_bf16 v[126:129], v[154:157], v[186:189], v[126:129]
	v_mfma_f32_16x16x32_bf16 v[114:117], v[142:145], v[190:193], v[114:117]
	v_mfma_f32_16x16x32_bf16 v[114:117], v[146:149], v[194:197], v[114:117]
	v_mfma_f32_16x16x32_bf16 v[110:113], v[150:153], v[190:193], v[110:113]
	v_mfma_f32_16x16x32_bf16 v[110:113], v[154:157], v[194:197], v[110:113]
	v_mfma_f32_16x16x32_bf16 v[98:101], v[142:145], v[198:201], v[98:101]
	v_mfma_f32_16x16x32_bf16 v[98:101], v[146:149], v[202:205], v[98:101]
	v_mfma_f32_16x16x32_bf16 v[94:97], v[150:153], v[198:201], v[94:97]
	v_mfma_f32_16x16x32_bf16 v[94:97], v[154:157], v[202:205], v[94:97]
	v_mfma_f32_16x16x32_bf16 v[82:85], v[142:145], v[206:209], v[82:85]
	v_mfma_f32_16x16x32_bf16 v[82:85], v[146:149], v[210:213], v[82:85]
	v_mfma_f32_16x16x32_bf16 v[78:81], v[150:153], v[206:209], v[78:81]
	v_mfma_f32_16x16x32_bf16 v[78:81], v[154:157], v[210:213], v[78:81]
	v_mfma_f32_16x16x32_bf16 v[122:125], v[158:161], v[182:185], v[122:125]
	v_mfma_f32_16x16x32_bf16 v[122:125], v[162:165], v[186:189], v[122:125]
	v_mfma_f32_16x16x32_bf16 v[118:121], v[166:169], v[182:185], v[118:121]
	v_mfma_f32_16x16x32_bf16 v[118:121], v[170:173], v[186:189], v[118:121]
	v_mfma_f32_16x16x32_bf16 v[106:109], v[158:161], v[190:193], v[106:109]
	v_mfma_f32_16x16x32_bf16 v[106:109], v[162:165], v[194:197], v[106:109]
	v_mfma_f32_16x16x32_bf16 v[102:105], v[166:169], v[190:193], v[102:105]
	v_mfma_f32_16x16x32_bf16 v[102:105], v[170:173], v[194:197], v[102:105]
	v_mfma_f32_16x16x32_bf16 v[90:93], v[158:161], v[198:201], v[90:93]
	v_mfma_f32_16x16x32_bf16 v[90:93], v[162:165], v[202:205], v[90:93]
	v_mfma_f32_16x16x32_bf16 v[86:89], v[166:169], v[198:201], v[86:89]
	v_mfma_f32_16x16x32_bf16 v[86:89], v[170:173], v[202:205], v[86:89]
	v_mfma_f32_16x16x32_bf16 v[74:77], v[158:161], v[206:209], v[74:77]
	v_mfma_f32_16x16x32_bf16 v[74:77], v[162:165], v[210:213], v[74:77]
	v_mfma_f32_16x16x32_bf16 v[70:73], v[166:169], v[206:209], v[70:73]
	v_mfma_f32_16x16x32_bf16 v[70:73], v[170:173], v[210:213], v[70:73]
	s_barrier
	s_setprio 0
	s_add_i32 s24, s48, s30
	v_lshl_add_u64 v[174:175], v[174:175], 0, s[92:93]
	s_mov_b32 m0, s24
	ds_read_b128 v[182:185], v251 offset:49152
	ds_read_b128 v[186:189], v251 offset:50176
	ds_read_b128 v[190:193], v251 offset:51200
	ds_read_b128 v[194:197], v251 offset:52224
	ds_read_b128 v[198:201], v251 offset:53248
	ds_read_b128 v[202:205], v251 offset:54272
	ds_read_b128 v[206:209], v251 offset:55296
	ds_read_b128 v[210:213], v251 offset:56320
	global_load_lds_dwordx4 v[174:175], off
	v_lshl_add_u64 v[174:175], v[214:215], 0, s[92:93]
	s_add_i32 m0, s24, 0x2000
	s_add_i32 s24, s49, s30
	global_load_lds_dwordx4 v[174:175], off
	v_lshl_add_u64 v[174:175], v[216:217], 0, s[92:93]
	s_mov_b32 m0, s24
	s_nop 0
	global_load_lds_dwordx4 v[174:175], off
	v_lshl_add_u64 v[174:175], v[218:219], 0, s[92:93]
	s_add_i32 m0, s24, 0x2000
	s_nop 0
	global_load_lds_dwordx4 v[174:175], off
	v_lshl_add_u64 v[174:175], v[220:221], 0, s[92:93]
	s_mov_b32 m0, s37
	s_nop 0
	global_load_lds_dwordx4 v[174:175], off
	v_lshl_add_u64 v[174:175], v[222:223], 0, s[92:93]
	s_mov_b32 m0, s38
	s_nop 0
	global_load_lds_dwordx4 v[174:175], off
	s_waitcnt vmcnt(8)
	s_waitcnt lgkmcnt(0)
	s_setprio 1
	s_barrier
	v_mfma_f32_16x16x32_bf16 v[66:69], v[142:145], v[182:185], v[66:69]
	v_mfma_f32_16x16x32_bf16 v[66:69], v[146:149], v[186:189], v[66:69]
	v_mfma_f32_16x16x32_bf16 v[62:65], v[150:153], v[182:185], v[62:65]
	v_mfma_f32_16x16x32_bf16 v[62:65], v[154:157], v[186:189], v[62:65]
	v_mfma_f32_16x16x32_bf16 v[50:53], v[142:145], v[190:193], v[50:53]
	v_mfma_f32_16x16x32_bf16 v[50:53], v[146:149], v[194:197], v[50:53]
	v_mfma_f32_16x16x32_bf16 v[46:49], v[150:153], v[190:193], v[46:49]
	v_mfma_f32_16x16x32_bf16 v[46:49], v[154:157], v[194:197], v[46:49]
	v_mfma_f32_16x16x32_bf16 v[34:37], v[142:145], v[198:201], v[34:37]
	v_mfma_f32_16x16x32_bf16 v[34:37], v[146:149], v[202:205], v[34:37]
	v_mfma_f32_16x16x32_bf16 v[30:33], v[150:153], v[198:201], v[30:33]
	v_mfma_f32_16x16x32_bf16 v[30:33], v[154:157], v[202:205], v[30:33]
	v_mfma_f32_16x16x32_bf16 v[18:21], v[142:145], v[206:209], v[18:21]
	v_mfma_f32_16x16x32_bf16 v[18:21], v[146:149], v[210:213], v[18:21]
	v_mfma_f32_16x16x32_bf16 v[10:13], v[150:153], v[206:209], v[10:13]
	v_mfma_f32_16x16x32_bf16 v[10:13], v[154:157], v[210:213], v[10:13]
	v_mfma_f32_16x16x32_bf16 v[58:61], v[158:161], v[182:185], v[58:61]
	v_mfma_f32_16x16x32_bf16 v[58:61], v[162:165], v[186:189], v[58:61]
	v_mfma_f32_16x16x32_bf16 v[54:57], v[166:169], v[182:185], v[54:57]
	v_mfma_f32_16x16x32_bf16 v[54:57], v[170:173], v[186:189], v[54:57]
	v_mfma_f32_16x16x32_bf16 v[42:45], v[158:161], v[190:193], v[42:45]
	v_mfma_f32_16x16x32_bf16 v[42:45], v[162:165], v[194:197], v[42:45]
	v_mfma_f32_16x16x32_bf16 v[38:41], v[166:169], v[190:193], v[38:41]
	v_mfma_f32_16x16x32_bf16 v[38:41], v[170:173], v[194:197], v[38:41]
	v_mfma_f32_16x16x32_bf16 v[26:29], v[158:161], v[198:201], v[26:29]
	v_mfma_f32_16x16x32_bf16 v[26:29], v[162:165], v[202:205], v[26:29]
	v_mfma_f32_16x16x32_bf16 v[22:25], v[166:169], v[198:201], v[22:25]
	v_mfma_f32_16x16x32_bf16 v[22:25], v[170:173], v[202:205], v[22:25]
	v_mfma_f32_16x16x32_bf16 v[6:9], v[158:161], v[206:209], v[6:9]
	v_mfma_f32_16x16x32_bf16 v[6:9], v[162:165], v[210:213], v[6:9]
	v_mfma_f32_16x16x32_bf16 v[2:5], v[166:169], v[206:209], v[2:5]
	v_mfma_f32_16x16x32_bf16 v[2:5], v[170:173], v[210:213], v[2:5]
	s_barrier
	s_setprio 0
	s_add_u32 s22, s22, 0x100
	s_addc_u32 s23, s23, 0
	s_add_u32 s45, s45, 0x100
	s_addc_u32 s46, s46, 0
	s_cmp_ge_u32 s47, s39
	s_mov_b32 s24, s47
	s_cbranch_scc1 .Lpeel_exit_2
.LBB0_637:
	s_add_i32 s47, s24, 2
	s_add_u32 s48, s22, 0x80
	s_addc_u32 s25, s23, 0
	s_add_i32 s50, 0, 0x10000
	s_cmp_eq_u32 s40, s24
	s_cselect_b32 s25, s7, s25
	s_cselect_b32 s24, s6, s48
	v_add_u32_e32 v135, s50, v249
	s_cselect_b32 s49, s21, s46
	s_cselect_b32 s48, s20, s45
	s_add_i32 s51, 0, 0x14000
	ds_read_b128 v[142:145], v135
	ds_read_b128 v[146:149], v135 offset:1024
	ds_read_b128 v[150:153], v135 offset:2048
	ds_read_b128 v[154:157], v135 offset:3072
	v_add_u32_e32 v135, s51, v249
	ds_read_b128 v[158:161], v135
	ds_read_b128 v[162:165], v135 offset:1024
	ds_read_b128 v[166:169], v135 offset:2048
	ds_read_b128 v[170:173], v135 offset:3072
	v_lshl_add_u64 v[174:175], s[22:23], 0, v[138:139]
	s_add_i32 m0, s31, 0xc000
	ds_read_b128 v[182:185], v251
	ds_read_b128 v[186:189], v251 offset:1024
	ds_read_b128 v[190:193], v251 offset:2048
	ds_read_b128 v[194:197], v251 offset:3072
	ds_read_b128 v[198:201], v251 offset:4096
	ds_read_b128 v[202:205], v251 offset:5120
	ds_read_b128 v[206:209], v251 offset:6144
	ds_read_b128 v[210:213], v251 offset:7168
	global_load_lds_dwordx4 v[174:175], off
	v_lshl_add_u64 v[174:175], s[22:23], 0, v[140:141]
	s_add_i32 m0, s31, 0xe000
	s_nop 0
	global_load_lds_dwordx4 v[174:175], off
	s_waitcnt vmcnt(8)
	s_waitcnt lgkmcnt(0)
	s_setprio 1
	s_barrier
	v_mfma_f32_16x16x32_bf16 v[130:133], v[142:145], v[182:185], v[130:133]
	v_mfma_f32_16x16x32_bf16 v[130:133], v[146:149], v[186:189], v[130:133]
	v_mfma_f32_16x16x32_bf16 v[126:129], v[150:153], v[182:185], v[126:129]
	v_mfma_f32_16x16x32_bf16 v[126:129], v[154:157], v[186:189], v[126:129]
	v_mfma_f32_16x16x32_bf16 v[114:117], v[142:145], v[190:193], v[114:117]
	v_mfma_f32_16x16x32_bf16 v[114:117], v[146:149], v[194:197], v[114:117]
	v_mfma_f32_16x16x32_bf16 v[110:113], v[150:153], v[190:193], v[110:113]
	v_mfma_f32_16x16x32_bf16 v[110:113], v[154:157], v[194:197], v[110:113]
	v_mfma_f32_16x16x32_bf16 v[98:101], v[142:145], v[198:201], v[98:101]
	v_mfma_f32_16x16x32_bf16 v[98:101], v[146:149], v[202:205], v[98:101]
	v_mfma_f32_16x16x32_bf16 v[94:97], v[150:153], v[198:201], v[94:97]
	v_mfma_f32_16x16x32_bf16 v[94:97], v[154:157], v[202:205], v[94:97]
	v_mfma_f32_16x16x32_bf16 v[82:85], v[142:145], v[206:209], v[82:85]
	v_mfma_f32_16x16x32_bf16 v[82:85], v[146:149], v[210:213], v[82:85]
	v_mfma_f32_16x16x32_bf16 v[78:81], v[150:153], v[206:209], v[78:81]
	v_mfma_f32_16x16x32_bf16 v[78:81], v[154:157], v[210:213], v[78:81]
	v_mfma_f32_16x16x32_bf16 v[122:125], v[158:161], v[182:185], v[122:125]
	v_mfma_f32_16x16x32_bf16 v[122:125], v[162:165], v[186:189], v[122:125]
	v_mfma_f32_16x16x32_bf16 v[118:121], v[166:169], v[182:185], v[118:121]
	v_mfma_f32_16x16x32_bf16 v[118:121], v[170:173], v[186:189], v[118:121]
	v_mfma_f32_16x16x32_bf16 v[106:109], v[158:161], v[190:193], v[106:109]
	v_mfma_f32_16x16x32_bf16 v[106:109], v[162:165], v[194:197], v[106:109]
	v_mfma_f32_16x16x32_bf16 v[102:105], v[166:169], v[190:193], v[102:105]
	v_mfma_f32_16x16x32_bf16 v[102:105], v[170:173], v[194:197], v[102:105]
	v_mfma_f32_16x16x32_bf16 v[90:93], v[158:161], v[198:201], v[90:93]
	v_mfma_f32_16x16x32_bf16 v[90:93], v[162:165], v[202:205], v[90:93]
	v_mfma_f32_16x16x32_bf16 v[86:89], v[166:169], v[198:201], v[86:89]
	v_mfma_f32_16x16x32_bf16 v[86:89], v[170:173], v[202:205], v[86:89]
	v_mfma_f32_16x16x32_bf16 v[74:77], v[158:161], v[206:209], v[74:77]
	v_mfma_f32_16x16x32_bf16 v[74:77], v[162:165], v[210:213], v[74:77]
	v_mfma_f32_16x16x32_bf16 v[70:73], v[166:169], v[206:209], v[70:73]
	v_mfma_f32_16x16x32_bf16 v[70:73], v[170:173], v[210:213], v[70:73]
	s_barrier
	s_setprio 0
	s_add_i32 s50, s50, s30
	v_lshl_add_u64 v[174:175], s[48:49], 0, v[0:1]
	s_mov_b32 m0, s50
	ds_read_b128 v[182:185], v251 offset:16384
	ds_read_b128 v[186:189], v251 offset:17408
	ds_read_b128 v[190:193], v251 offset:18432
	ds_read_b128 v[194:197], v251 offset:19456
	ds_read_b128 v[198:201], v251 offset:20480
	ds_read_b128 v[202:205], v251 offset:21504
	ds_read_b128 v[206:209], v251 offset:22528
	ds_read_b128 v[210:213], v251 offset:23552
	global_load_lds_dwordx4 v[174:175], off
	s_add_i32 m0, s50, 0x2000
	v_lshl_add_u64 v[214:215], s[48:49], 0, v[14:15]
	s_add_u32 s48, s48, s10
	s_addc_u32 s49, s49, 0
	s_add_i32 s50, s51, s30
	global_load_lds_dwordx4 v[214:215], off
	v_lshl_add_u64 v[216:217], s[48:49], 0, v[0:1]
	s_mov_b32 m0, s50
	v_lshl_add_u64 v[218:219], s[48:49], 0, v[14:15]
	global_load_lds_dwordx4 v[216:217], off
	s_add_i32 m0, s50, 0x2000
	v_lshl_add_u64 v[220:221], s[24:25], 0, v[0:1]
	global_load_lds_dwordx4 v[218:219], off
	s_mov_b32 m0, s31
	v_lshl_add_u64 v[222:223], s[24:25], 0, v[14:15]
	global_load_lds_dwordx4 v[220:221], off
	s_mov_b32 m0, s34
	s_nop 0
	global_load_lds_dwordx4 v[222:223], off
	s_waitcnt vmcnt(8)
	s_waitcnt lgkmcnt(0)
	s_setprio 1
	s_barrier
	v_mfma_f32_16x16x32_bf16 v[66:69], v[142:145], v[182:185], v[66:69]
	v_mfma_f32_16x16x32_bf16 v[66:69], v[146:149], v[186:189], v[66:69]
	v_mfma_f32_16x16x32_bf16 v[62:65], v[150:153], v[182:185], v[62:65]
	v_mfma_f32_16x16x32_bf16 v[62:65], v[154:157], v[186:189], v[62:65]
	v_mfma_f32_16x16x32_bf16 v[50:53], v[142:145], v[190:193], v[50:53]
	v_mfma_f32_16x16x32_bf16 v[50:53], v[146:149], v[194:197], v[50:53]
	v_mfma_f32_16x16x32_bf16 v[46:49], v[150:153], v[190:193], v[46:49]
	v_mfma_f32_16x16x32_bf16 v[46:49], v[154:157], v[194:197], v[46:49]
	v_mfma_f32_16x16x32_bf16 v[34:37], v[142:145], v[198:201], v[34:37]
	v_mfma_f32_16x16x32_bf16 v[34:37], v[146:149], v[202:205], v[34:37]
	v_mfma_f32_16x16x32_bf16 v[30:33], v[150:153], v[198:201], v[30:33]
	v_mfma_f32_16x16x32_bf16 v[30:33], v[154:157], v[202:205], v[30:33]
	v_mfma_f32_16x16x32_bf16 v[18:21], v[142:145], v[206:209], v[18:21]
	v_mfma_f32_16x16x32_bf16 v[18:21], v[146:149], v[210:213], v[18:21]
	v_mfma_f32_16x16x32_bf16 v[10:13], v[150:153], v[206:209], v[10:13]
	v_mfma_f32_16x16x32_bf16 v[10:13], v[154:157], v[210:213], v[10:13]
	v_mfma_f32_16x16x32_bf16 v[58:61], v[158:161], v[182:185], v[58:61]
	v_mfma_f32_16x16x32_bf16 v[58:61], v[162:165], v[186:189], v[58:61]
	v_mfma_f32_16x16x32_bf16 v[54:57], v[166:169], v[182:185], v[54:57]
	v_mfma_f32_16x16x32_bf16 v[54:57], v[170:173], v[186:189], v[54:57]
	v_mfma_f32_16x16x32_bf16 v[42:45], v[158:161], v[190:193], v[42:45]
	v_mfma_f32_16x16x32_bf16 v[42:45], v[162:165], v[194:197], v[42:45]
	v_mfma_f32_16x16x32_bf16 v[38:41], v[166:169], v[190:193], v[38:41]
	v_mfma_f32_16x16x32_bf16 v[38:41], v[170:173], v[194:197], v[38:41]
	v_mfma_f32_16x16x32_bf16 v[26:29], v[158:161], v[198:201], v[26:29]
	v_mfma_f32_16x16x32_bf16 v[26:29], v[162:165], v[202:205], v[26:29]
	v_mfma_f32_16x16x32_bf16 v[22:25], v[166:169], v[198:201], v[22:25]
	v_mfma_f32_16x16x32_bf16 v[22:25], v[170:173], v[202:205], v[22:25]
	v_mfma_f32_16x16x32_bf16 v[6:9], v[158:161], v[206:209], v[6:9]
	v_mfma_f32_16x16x32_bf16 v[6:9], v[162:165], v[210:213], v[6:9]
	v_mfma_f32_16x16x32_bf16 v[2:5], v[166:169], v[206:209], v[2:5]
	v_mfma_f32_16x16x32_bf16 v[2:5], v[170:173], v[210:213], v[2:5]
	s_barrier
	s_setprio 0
	s_add_i32 s48, 0, 0x18000
	v_add_u32_e32 v135, s48, v249
	s_add_i32 s49, 0, 0x1c000
	ds_read_b128 v[142:145], v135
	ds_read_b128 v[146:149], v135 offset:1024
	ds_read_b128 v[150:153], v135 offset:2048
	ds_read_b128 v[154:157], v135 offset:3072
	v_add_u32_e32 v135, s49, v249
	ds_read_b128 v[158:161], v135
	ds_read_b128 v[162:165], v135 offset:1024
	ds_read_b128 v[166:169], v135 offset:2048
	ds_read_b128 v[170:173], v135 offset:3072
	s_add_u32 s24, s24, s10
	s_addc_u32 s25, s25, 0
	s_mov_b32 m0, s35
	v_lshl_add_u64 v[224:225], s[24:25], 0, v[0:1]
	ds_read_b128 v[182:185], v251 offset:32768
	ds_read_b128 v[186:189], v251 offset:33792
	ds_read_b128 v[190:193], v251 offset:34816
	ds_read_b128 v[194:197], v251 offset:35840
	ds_read_b128 v[198:201], v251 offset:36864
	ds_read_b128 v[202:205], v251 offset:37888
	ds_read_b128 v[206:209], v251 offset:38912
	ds_read_b128 v[210:213], v251 offset:39936
	global_load_lds_dwordx4 v[224:225], off
	v_lshl_add_u64 v[224:225], s[24:25], 0, v[14:15]
	s_mov_b32 m0, s36
	s_nop 0
	global_load_lds_dwordx4 v[224:225], off
	s_waitcnt vmcnt(8)
	s_waitcnt lgkmcnt(0)
	s_setprio 1
	s_barrier
	v_mfma_f32_16x16x32_bf16 v[130:133], v[142:145], v[182:185], v[130:133]
	v_mfma_f32_16x16x32_bf16 v[130:133], v[146:149], v[186:189], v[130:133]
	v_mfma_f32_16x16x32_bf16 v[126:129], v[150:153], v[182:185], v[126:129]
	v_mfma_f32_16x16x32_bf16 v[126:129], v[154:157], v[186:189], v[126:129]
	v_mfma_f32_16x16x32_bf16 v[114:117], v[142:145], v[190:193], v[114:117]
	v_mfma_f32_16x16x32_bf16 v[114:117], v[146:149], v[194:197], v[114:117]
	v_mfma_f32_16x16x32_bf16 v[110:113], v[150:153], v[190:193], v[110:113]
	v_mfma_f32_16x16x32_bf16 v[110:113], v[154:157], v[194:197], v[110:113]
	v_mfma_f32_16x16x32_bf16 v[98:101], v[142:145], v[198:201], v[98:101]
	v_mfma_f32_16x16x32_bf16 v[98:101], v[146:149], v[202:205], v[98:101]
	v_mfma_f32_16x16x32_bf16 v[94:97], v[150:153], v[198:201], v[94:97]
	v_mfma_f32_16x16x32_bf16 v[94:97], v[154:157], v[202:205], v[94:97]
	v_mfma_f32_16x16x32_bf16 v[82:85], v[142:145], v[206:209], v[82:85]
	v_mfma_f32_16x16x32_bf16 v[82:85], v[146:149], v[210:213], v[82:85]
	v_mfma_f32_16x16x32_bf16 v[78:81], v[150:153], v[206:209], v[78:81]
	v_mfma_f32_16x16x32_bf16 v[78:81], v[154:157], v[210:213], v[78:81]
	v_mfma_f32_16x16x32_bf16 v[122:125], v[158:161], v[182:185], v[122:125]
	v_mfma_f32_16x16x32_bf16 v[122:125], v[162:165], v[186:189], v[122:125]
	v_mfma_f32_16x16x32_bf16 v[118:121], v[166:169], v[182:185], v[118:121]
	v_mfma_f32_16x16x32_bf16 v[118:121], v[170:173], v[186:189], v[118:121]
	v_mfma_f32_16x16x32_bf16 v[106:109], v[158:161], v[190:193], v[106:109]
	v_mfma_f32_16x16x32_bf16 v[106:109], v[162:165], v[194:197], v[106:109]
	v_mfma_f32_16x16x32_bf16 v[102:105], v[166:169], v[190:193], v[102:105]
	v_mfma_f32_16x16x32_bf16 v[102:105], v[170:173], v[194:197], v[102:105]
	v_mfma_f32_16x16x32_bf16 v[90:93], v[158:161], v[198:201], v[90:93]
	v_mfma_f32_16x16x32_bf16 v[90:93], v[162:165], v[202:205], v[90:93]
	v_mfma_f32_16x16x32_bf16 v[86:89], v[166:169], v[198:201], v[86:89]
	v_mfma_f32_16x16x32_bf16 v[86:89], v[170:173], v[202:205], v[86:89]
	v_mfma_f32_16x16x32_bf16 v[74:77], v[158:161], v[206:209], v[74:77]
	v_mfma_f32_16x16x32_bf16 v[74:77], v[162:165], v[210:213], v[74:77]
	v_mfma_f32_16x16x32_bf16 v[70:73], v[166:169], v[206:209], v[70:73]
	v_mfma_f32_16x16x32_bf16 v[70:73], v[170:173], v[210:213], v[70:73]
	s_barrier
	s_setprio 0
	s_add_i32 s24, s48, s30
	v_lshl_add_u64 v[174:175], v[174:175], 0, s[92:93]
	s_mov_b32 m0, s24
	ds_read_b128 v[182:185], v251 offset:49152
	ds_read_b128 v[186:189], v251 offset:50176
	ds_read_b128 v[190:193], v251 offset:51200
	ds_read_b128 v[194:197], v251 offset:52224
	ds_read_b128 v[198:201], v251 offset:53248
	ds_read_b128 v[202:205], v251 offset:54272
	ds_read_b128 v[206:209], v251 offset:55296
	ds_read_b128 v[210:213], v251 offset:56320
	global_load_lds_dwordx4 v[174:175], off
	v_lshl_add_u64 v[174:175], v[214:215], 0, s[92:93]
	s_add_i32 m0, s24, 0x2000
	s_add_i32 s24, s49, s30
	global_load_lds_dwordx4 v[174:175], off
	v_lshl_add_u64 v[174:175], v[216:217], 0, s[92:93]
	s_mov_b32 m0, s24
	s_nop 0
	global_load_lds_dwordx4 v[174:175], off
	v_lshl_add_u64 v[174:175], v[218:219], 0, s[92:93]
	s_add_i32 m0, s24, 0x2000
	s_nop 0
	global_load_lds_dwordx4 v[174:175], off
	v_lshl_add_u64 v[174:175], v[220:221], 0, s[92:93]
	s_mov_b32 m0, s37
	s_nop 0
	global_load_lds_dwordx4 v[174:175], off
	v_lshl_add_u64 v[174:175], v[222:223], 0, s[92:93]
	s_mov_b32 m0, s38
	s_nop 0
	global_load_lds_dwordx4 v[174:175], off
	s_waitcnt vmcnt(8)
	s_waitcnt lgkmcnt(0)
	s_setprio 1
	s_barrier
	v_mfma_f32_16x16x32_bf16 v[66:69], v[142:145], v[182:185], v[66:69]
	v_mfma_f32_16x16x32_bf16 v[66:69], v[146:149], v[186:189], v[66:69]
	v_mfma_f32_16x16x32_bf16 v[62:65], v[150:153], v[182:185], v[62:65]
	v_mfma_f32_16x16x32_bf16 v[62:65], v[154:157], v[186:189], v[62:65]
	v_mfma_f32_16x16x32_bf16 v[50:53], v[142:145], v[190:193], v[50:53]
	v_mfma_f32_16x16x32_bf16 v[50:53], v[146:149], v[194:197], v[50:53]
	v_mfma_f32_16x16x32_bf16 v[46:49], v[150:153], v[190:193], v[46:49]
	v_mfma_f32_16x16x32_bf16 v[46:49], v[154:157], v[194:197], v[46:49]
	v_mfma_f32_16x16x32_bf16 v[34:37], v[142:145], v[198:201], v[34:37]
	v_mfma_f32_16x16x32_bf16 v[34:37], v[146:149], v[202:205], v[34:37]
	v_mfma_f32_16x16x32_bf16 v[30:33], v[150:153], v[198:201], v[30:33]
	v_mfma_f32_16x16x32_bf16 v[30:33], v[154:157], v[202:205], v[30:33]
	v_mfma_f32_16x16x32_bf16 v[18:21], v[142:145], v[206:209], v[18:21]
	v_mfma_f32_16x16x32_bf16 v[18:21], v[146:149], v[210:213], v[18:21]
	v_mfma_f32_16x16x32_bf16 v[10:13], v[150:153], v[206:209], v[10:13]
	v_mfma_f32_16x16x32_bf16 v[10:13], v[154:157], v[210:213], v[10:13]
	v_mfma_f32_16x16x32_bf16 v[58:61], v[158:161], v[182:185], v[58:61]
	v_mfma_f32_16x16x32_bf16 v[58:61], v[162:165], v[186:189], v[58:61]
	v_mfma_f32_16x16x32_bf16 v[54:57], v[166:169], v[182:185], v[54:57]
	v_mfma_f32_16x16x32_bf16 v[54:57], v[170:173], v[186:189], v[54:57]
	v_mfma_f32_16x16x32_bf16 v[42:45], v[158:161], v[190:193], v[42:45]
	v_mfma_f32_16x16x32_bf16 v[42:45], v[162:165], v[194:197], v[42:45]
	v_mfma_f32_16x16x32_bf16 v[38:41], v[166:169], v[190:193], v[38:41]
	v_mfma_f32_16x16x32_bf16 v[38:41], v[170:173], v[194:197], v[38:41]
	v_mfma_f32_16x16x32_bf16 v[26:29], v[158:161], v[198:201], v[26:29]
	v_mfma_f32_16x16x32_bf16 v[26:29], v[162:165], v[202:205], v[26:29]
	v_mfma_f32_16x16x32_bf16 v[22:25], v[166:169], v[198:201], v[22:25]
	v_mfma_f32_16x16x32_bf16 v[22:25], v[170:173], v[202:205], v[22:25]
	v_mfma_f32_16x16x32_bf16 v[6:9], v[158:161], v[206:209], v[6:9]
	v_mfma_f32_16x16x32_bf16 v[6:9], v[162:165], v[210:213], v[6:9]
	v_mfma_f32_16x16x32_bf16 v[2:5], v[166:169], v[206:209], v[2:5]
	v_mfma_f32_16x16x32_bf16 v[2:5], v[170:173], v[210:213], v[2:5]
	s_barrier
	s_setprio 0
	s_add_u32 s22, s22, 0x100
	s_addc_u32 s23, s23, 0
	s_add_u32 s45, s45, 0x100
	s_addc_u32 s46, s46, 0
	s_cmp_ge_u32 s47, s39
	s_mov_b32 s24, s47
	s_cbranch_scc0 .LBB0_637

.Lg3_join_w1_pl3:
	s_waitcnt lgkmcnt(0)
	s_setprio 1
	s_barrier
	v_mfma_f32_16x16x32_bf16 v[130:133], v[134:137], v[194:197], 0
	v_mfma_f32_16x16x32_bf16 v[130:133], v[148:151], v[198:201], v[130:133]
	v_mfma_f32_16x16x32_bf16 v[122:125], v[152:155], v[194:197], 0
	v_mfma_f32_16x16x32_bf16 v[122:125], v[156:159], v[198:201], v[122:125]
	v_mfma_f32_16x16x32_bf16 v[114:117], v[134:137], v[202:205], 0
	v_mfma_f32_16x16x32_bf16 v[114:117], v[148:151], v[206:209], v[114:117]
	v_mfma_f32_16x16x32_bf16 v[106:109], v[152:155], v[202:205], 0
	v_mfma_f32_16x16x32_bf16 v[106:109], v[156:159], v[206:209], v[106:109]
	v_mfma_f32_16x16x32_bf16 v[98:101], v[134:137], v[210:213], 0
	v_mfma_f32_16x16x32_bf16 v[98:101], v[148:151], v[214:217], v[98:101]
	v_mfma_f32_16x16x32_bf16 v[90:93], v[152:155], v[210:213], 0
	v_mfma_f32_16x16x32_bf16 v[90:93], v[156:159], v[214:217], v[90:93]
	v_mfma_f32_16x16x32_bf16 v[82:85], v[134:137], v[218:221], 0
	v_mfma_f32_16x16x32_bf16 v[82:85], v[148:151], v[222:225], v[82:85]
	v_mfma_f32_16x16x32_bf16 v[74:77], v[152:155], v[218:221], 0
	v_mfma_f32_16x16x32_bf16 v[74:77], v[156:159], v[222:225], v[74:77]
	v_mfma_f32_16x16x32_bf16 v[126:129], v[160:163], v[194:197], 0
	v_mfma_f32_16x16x32_bf16 v[126:129], v[182:185], v[198:201], v[126:129]
	v_mfma_f32_16x16x32_bf16 v[118:121], v[186:189], v[194:197], 0
	v_mfma_f32_16x16x32_bf16 v[118:121], v[190:193], v[198:201], v[118:121]
	v_mfma_f32_16x16x32_bf16 v[110:113], v[160:163], v[202:205], 0
	v_mfma_f32_16x16x32_bf16 v[110:113], v[182:185], v[206:209], v[110:113]
	v_mfma_f32_16x16x32_bf16 v[102:105], v[186:189], v[202:205], 0
	v_mfma_f32_16x16x32_bf16 v[102:105], v[190:193], v[206:209], v[102:105]
	v_mfma_f32_16x16x32_bf16 v[94:97], v[160:163], v[210:213], 0
	v_mfma_f32_16x16x32_bf16 v[94:97], v[182:185], v[214:217], v[94:97]
	v_mfma_f32_16x16x32_bf16 v[86:89], v[186:189], v[210:213], 0
	v_mfma_f32_16x16x32_bf16 v[86:89], v[190:193], v[214:217], v[86:89]
	v_mfma_f32_16x16x32_bf16 v[78:81], v[160:163], v[218:221], 0
	v_mfma_f32_16x16x32_bf16 v[78:81], v[182:185], v[222:225], v[78:81]
	v_mfma_f32_16x16x32_bf16 v[70:73], v[186:189], v[218:221], 0
	v_mfma_f32_16x16x32_bf16 v[70:73], v[190:193], v[222:225], v[70:73]
	s_barrier
	s_setprio 0
	s_add_i32 s41, s41, s13
	v_lshl_add_u64 v[226:227], s[20:21], 0, v[0:1]
	s_mov_b32 m0, s41
	ds_read_b128 v[194:197], v175 offset:16384
	ds_read_b128 v[198:201], v175 offset:17408
	ds_read_b128 v[202:205], v175 offset:18432
	ds_read_b128 v[206:209], v175 offset:19456
	ds_read_b128 v[210:213], v175 offset:20480
	ds_read_b128 v[214:217], v175 offset:21504
	ds_read_b128 v[218:221], v175 offset:22528
	ds_read_b128 v[222:225], v175 offset:23552
	global_load_lds_dwordx4 v[226:227], off
	s_add_i32 m0, s41, 0x2000
	s_add_u32 s42, s20, 0x40000
	v_lshl_add_u64 v[228:229], s[20:21], 0, v[14:15]
	s_addc_u32 s43, s21, 0
	s_add_i32 s41, s44, s13
	global_load_lds_dwordx4 v[228:229], off
	v_lshl_add_u64 v[230:231], s[42:43], 0, v[0:1]
	s_mov_b32 m0, s41
	v_lshl_add_u64 v[232:233], s[22:23], 0, v[138:139]
	global_load_lds_dwordx4 v[230:231], off
	v_lshl_add_u64 v[230:231], s[42:43], 0, v[14:15]
	s_add_i32 m0, s41, 0x2000
	s_nop 0
	global_load_lds_dwordx4 v[230:231], off
	v_lshl_add_u64 v[230:231], s[22:23], 0, v[140:141]
	s_mov_b32 m0, s26
	s_nop 0
	global_load_lds_dwordx4 v[230:231], off
	s_mov_b32 m0, s27
	s_nop 0
	global_load_lds_dwordx4 v[232:233], off
	s_cmp_eq_i32 s40, -2
	s_cselect_b32 s98, s2, 0
	s_cmp_lg_u32 s98, 0
	s_cbranch_scc1 .Lg3_relax_w2_pl3
	s_waitcnt vmcnt(8)
	s_branch .Lg3_join_w2_pl3

.Lg3_join_w2_pl3:
	s_waitcnt lgkmcnt(0)
	s_setprio 1
	s_barrier
	v_mfma_f32_16x16x32_bf16 v[66:69], v[134:137], v[194:197], 0
	v_mfma_f32_16x16x32_bf16 v[66:69], v[148:151], v[198:201], v[66:69]
	v_mfma_f32_16x16x32_bf16 v[58:61], v[152:155], v[194:197], 0
	v_mfma_f32_16x16x32_bf16 v[58:61], v[156:159], v[198:201], v[58:61]
	v_mfma_f32_16x16x32_bf16 v[50:53], v[134:137], v[202:205], 0
	v_mfma_f32_16x16x32_bf16 v[50:53], v[148:151], v[206:209], v[50:53]
	v_mfma_f32_16x16x32_bf16 v[42:45], v[152:155], v[202:205], 0
	v_mfma_f32_16x16x32_bf16 v[42:45], v[156:159], v[206:209], v[42:45]
	v_mfma_f32_16x16x32_bf16 v[34:37], v[134:137], v[210:213], 0
	v_mfma_f32_16x16x32_bf16 v[34:37], v[148:151], v[214:217], v[34:37]
	v_mfma_f32_16x16x32_bf16 v[26:29], v[152:155], v[210:213], 0
	v_mfma_f32_16x16x32_bf16 v[26:29], v[156:159], v[214:217], v[26:29]
	v_mfma_f32_16x16x32_bf16 v[18:21], v[134:137], v[218:221], 0
	v_mfma_f32_16x16x32_bf16 v[18:21], v[148:151], v[222:225], v[18:21]
	v_mfma_f32_16x16x32_bf16 v[6:9], v[152:155], v[218:221], 0
	v_mfma_f32_16x16x32_bf16 v[6:9], v[156:159], v[222:225], v[6:9]
	v_mfma_f32_16x16x32_bf16 v[62:65], v[160:163], v[194:197], 0
	v_mfma_f32_16x16x32_bf16 v[62:65], v[182:185], v[198:201], v[62:65]
	v_mfma_f32_16x16x32_bf16 v[54:57], v[186:189], v[194:197], 0
	v_mfma_f32_16x16x32_bf16 v[54:57], v[190:193], v[198:201], v[54:57]
	v_mfma_f32_16x16x32_bf16 v[46:49], v[160:163], v[202:205], 0
	v_mfma_f32_16x16x32_bf16 v[46:49], v[182:185], v[206:209], v[46:49]
	v_mfma_f32_16x16x32_bf16 v[38:41], v[186:189], v[202:205], 0
	v_mfma_f32_16x16x32_bf16 v[38:41], v[190:193], v[206:209], v[38:41]
	v_mfma_f32_16x16x32_bf16 v[30:33], v[160:163], v[210:213], 0
	v_mfma_f32_16x16x32_bf16 v[30:33], v[182:185], v[214:217], v[30:33]
	v_mfma_f32_16x16x32_bf16 v[22:25], v[186:189], v[210:213], 0
	v_mfma_f32_16x16x32_bf16 v[22:25], v[190:193], v[214:217], v[22:25]
	v_mfma_f32_16x16x32_bf16 v[10:13], v[160:163], v[218:221], 0
	v_mfma_f32_16x16x32_bf16 v[10:13], v[182:185], v[222:225], v[10:13]
	v_mfma_f32_16x16x32_bf16 v[2:5], v[186:189], v[218:221], 0
	v_mfma_f32_16x16x32_bf16 v[2:5], v[190:193], v[222:225], v[2:5]
	s_barrier
	s_setprio 0
	s_add_i32 s41, 0, 0x18000
	s_add_i32 s42, 0, 0x1c000
	v_add_u32_e32 v156, s41, v171
	v_add_u32_e32 v164, s42, v171
	ds_read_b128 v[134:137], v156
	ds_read_b128 v[148:151], v156 offset:1024
	ds_read_b128 v[152:155], v156 offset:2048
	ds_read_b128 v[156:159], v156 offset:3072
	ds_read_b128 v[160:163], v164
	ds_read_b128 v[182:185], v164 offset:1024
	ds_read_b128 v[186:189], v164 offset:2048
	ds_read_b128 v[190:193], v164 offset:3072
	s_add_u32 s22, s22, 0x40000
	s_addc_u32 s23, s23, 0
	s_mov_b32 m0, s28
	v_lshl_add_u64 v[234:235], s[22:23], 0, v[140:141]
	ds_read_b128 v[194:197], v175 offset:32768
	ds_read_b128 v[198:201], v175 offset:33792
	ds_read_b128 v[202:205], v175 offset:34816
	ds_read_b128 v[206:209], v175 offset:35840
	ds_read_b128 v[210:213], v175 offset:36864
	ds_read_b128 v[214:217], v175 offset:37888
	ds_read_b128 v[218:221], v175 offset:38912
	ds_read_b128 v[222:225], v175 offset:39936
	global_load_lds_dwordx4 v[234:235], off
	v_lshl_add_u64 v[234:235], s[22:23], 0, v[138:139]
	s_mov_b32 m0, s29
	s_nop 0
	global_load_lds_dwordx4 v[234:235], off
	s_waitcnt vmcnt(8)
	s_waitcnt lgkmcnt(0)
	s_setprio 1
	s_barrier
	v_mfma_f32_16x16x32_bf16 v[130:133], v[134:137], v[194:197], v[130:133]
	v_mfma_f32_16x16x32_bf16 v[130:133], v[148:151], v[198:201], v[130:133]
	v_mfma_f32_16x16x32_bf16 v[122:125], v[152:155], v[194:197], v[122:125]
	v_mfma_f32_16x16x32_bf16 v[122:125], v[156:159], v[198:201], v[122:125]
	v_mfma_f32_16x16x32_bf16 v[114:117], v[134:137], v[202:205], v[114:117]
	v_mfma_f32_16x16x32_bf16 v[114:117], v[148:151], v[206:209], v[114:117]
	v_mfma_f32_16x16x32_bf16 v[106:109], v[152:155], v[202:205], v[106:109]
	v_mfma_f32_16x16x32_bf16 v[106:109], v[156:159], v[206:209], v[106:109]
	v_mfma_f32_16x16x32_bf16 v[98:101], v[134:137], v[210:213], v[98:101]
	v_mfma_f32_16x16x32_bf16 v[98:101], v[148:151], v[214:217], v[98:101]
	v_mfma_f32_16x16x32_bf16 v[90:93], v[152:155], v[210:213], v[90:93]
	v_mfma_f32_16x16x32_bf16 v[90:93], v[156:159], v[214:217], v[90:93]
	v_mfma_f32_16x16x32_bf16 v[82:85], v[134:137], v[218:221], v[82:85]
	v_mfma_f32_16x16x32_bf16 v[82:85], v[148:151], v[222:225], v[82:85]
	v_mfma_f32_16x16x32_bf16 v[74:77], v[152:155], v[218:221], v[74:77]
	v_mfma_f32_16x16x32_bf16 v[74:77], v[156:159], v[222:225], v[74:77]
	v_mfma_f32_16x16x32_bf16 v[126:129], v[160:163], v[194:197], v[126:129]
	v_mfma_f32_16x16x32_bf16 v[126:129], v[182:185], v[198:201], v[126:129]
	v_mfma_f32_16x16x32_bf16 v[118:121], v[186:189], v[194:197], v[118:121]
	v_mfma_f32_16x16x32_bf16 v[118:121], v[190:193], v[198:201], v[118:121]
	v_mfma_f32_16x16x32_bf16 v[110:113], v[160:163], v[202:205], v[110:113]
	v_mfma_f32_16x16x32_bf16 v[110:113], v[182:185], v[206:209], v[110:113]
	v_mfma_f32_16x16x32_bf16 v[102:105], v[186:189], v[202:205], v[102:105]
	v_mfma_f32_16x16x32_bf16 v[102:105], v[190:193], v[206:209], v[102:105]
	v_mfma_f32_16x16x32_bf16 v[94:97], v[160:163], v[210:213], v[94:97]
	v_mfma_f32_16x16x32_bf16 v[94:97], v[182:185], v[214:217], v[94:97]
	v_mfma_f32_16x16x32_bf16 v[86:89], v[186:189], v[210:213], v[86:89]
	v_mfma_f32_16x16x32_bf16 v[86:89], v[190:193], v[214:217], v[86:89]
	v_mfma_f32_16x16x32_bf16 v[78:81], v[160:163], v[218:221], v[78:81]
	v_mfma_f32_16x16x32_bf16 v[78:81], v[182:185], v[222:225], v[78:81]
	v_mfma_f32_16x16x32_bf16 v[70:73], v[186:189], v[218:221], v[70:73]
	v_mfma_f32_16x16x32_bf16 v[70:73], v[190:193], v[222:225], v[70:73]
	s_barrier
	s_setprio 0
	s_add_i32 s22, s41, s13
	v_lshl_add_u64 v[226:227], v[226:227], 0, s[92:93]
	s_mov_b32 m0, s22
	ds_read_b128 v[194:197], v175 offset:49152
	ds_read_b128 v[198:201], v175 offset:50176
	ds_read_b128 v[202:205], v175 offset:51200
	ds_read_b128 v[206:209], v175 offset:52224
	ds_read_b128 v[210:213], v175 offset:53248
	ds_read_b128 v[214:217], v175 offset:54272
	ds_read_b128 v[218:221], v175 offset:55296
	ds_read_b128 v[222:225], v175 offset:56320
	global_load_lds_dwordx4 v[226:227], off
	s_add_i32 m0, s22, 0x2000
	s_add_u32 s20, s20, 0x40080
	v_lshl_add_u64 v[226:227], v[228:229], 0, s[92:93]
	s_addc_u32 s21, s21, 0
	s_add_i32 s22, s42, s13
	global_load_lds_dwordx4 v[226:227], off
	v_lshl_add_u64 v[226:227], s[20:21], 0, v[0:1]
	s_mov_b32 m0, s22
	s_nop 0
	global_load_lds_dwordx4 v[226:227], off
	v_lshl_add_u64 v[226:227], s[20:21], 0, v[14:15]
	s_add_i32 m0, s22, 0x2000
	s_nop 0
	global_load_lds_dwordx4 v[226:227], off
	v_lshl_add_u64 v[226:227], v[230:231], 0, s[92:93]
	s_mov_b32 m0, s30
	s_nop 0
	global_load_lds_dwordx4 v[226:227], off
	v_lshl_add_u64 v[226:227], v[232:233], 0, s[92:93]
	s_mov_b32 m0, s31
	s_nop 0
	global_load_lds_dwordx4 v[226:227], off
	s_waitcnt vmcnt(8)
	s_waitcnt lgkmcnt(0)
	s_setprio 1
	s_barrier
	v_mfma_f32_16x16x32_bf16 v[66:69], v[134:137], v[194:197], v[66:69]
	v_mfma_f32_16x16x32_bf16 v[66:69], v[148:151], v[198:201], v[66:69]
	v_mfma_f32_16x16x32_bf16 v[58:61], v[152:155], v[194:197], v[58:61]
	v_mfma_f32_16x16x32_bf16 v[58:61], v[156:159], v[198:201], v[58:61]
	v_mfma_f32_16x16x32_bf16 v[50:53], v[134:137], v[202:205], v[50:53]
	v_mfma_f32_16x16x32_bf16 v[50:53], v[148:151], v[206:209], v[50:53]
	v_mfma_f32_16x16x32_bf16 v[42:45], v[152:155], v[202:205], v[42:45]
	v_mfma_f32_16x16x32_bf16 v[42:45], v[156:159], v[206:209], v[42:45]
	v_mfma_f32_16x16x32_bf16 v[34:37], v[134:137], v[210:213], v[34:37]
	v_mfma_f32_16x16x32_bf16 v[34:37], v[148:151], v[214:217], v[34:37]
	v_mfma_f32_16x16x32_bf16 v[26:29], v[152:155], v[210:213], v[26:29]
	v_mfma_f32_16x16x32_bf16 v[26:29], v[156:159], v[214:217], v[26:29]
	v_mfma_f32_16x16x32_bf16 v[18:21], v[134:137], v[218:221], v[18:21]
	v_mfma_f32_16x16x32_bf16 v[18:21], v[148:151], v[222:225], v[18:21]
	v_mfma_f32_16x16x32_bf16 v[6:9], v[152:155], v[218:221], v[6:9]
	v_mfma_f32_16x16x32_bf16 v[6:9], v[156:159], v[222:225], v[6:9]
	v_mfma_f32_16x16x32_bf16 v[62:65], v[160:163], v[194:197], v[62:65]
	v_mfma_f32_16x16x32_bf16 v[62:65], v[182:185], v[198:201], v[62:65]
	v_mfma_f32_16x16x32_bf16 v[54:57], v[186:189], v[194:197], v[54:57]
	v_mfma_f32_16x16x32_bf16 v[54:57], v[190:193], v[198:201], v[54:57]
	v_mfma_f32_16x16x32_bf16 v[46:49], v[160:163], v[202:205], v[46:49]
	v_mfma_f32_16x16x32_bf16 v[46:49], v[182:185], v[206:209], v[46:49]
	v_mfma_f32_16x16x32_bf16 v[38:41], v[186:189], v[202:205], v[38:41]
	v_mfma_f32_16x16x32_bf16 v[38:41], v[190:193], v[206:209], v[38:41]
	v_mfma_f32_16x16x32_bf16 v[30:33], v[160:163], v[210:213], v[30:33]
	v_mfma_f32_16x16x32_bf16 v[30:33], v[182:185], v[214:217], v[30:33]
	v_mfma_f32_16x16x32_bf16 v[22:25], v[186:189], v[210:213], v[22:25]
	v_mfma_f32_16x16x32_bf16 v[22:25], v[190:193], v[214:217], v[22:25]
	v_mfma_f32_16x16x32_bf16 v[10:13], v[160:163], v[218:221], v[10:13]
	v_mfma_f32_16x16x32_bf16 v[10:13], v[182:185], v[222:225], v[10:13]
	v_mfma_f32_16x16x32_bf16 v[2:5], v[186:189], v[218:221], v[2:5]
	v_mfma_f32_16x16x32_bf16 v[2:5], v[190:193], v[222:225], v[2:5]
	s_barrier
	s_setprio 0
	s_add_i32 s40, s40, 2
	s_add_u32 s4, s4, 0x100
	s_addc_u32 s5, s5, 0
	s_add_u32 s38, s38, 0x100
	s_addc_u32 s39, s39, 0
	s_cmp_gt_u32 s40, 13
	s_cbranch_scc1 .Lpeel_exit_3

.Lg3_join_w1:
	s_waitcnt lgkmcnt(0)
	s_setprio 1
	s_barrier
	v_mfma_f32_16x16x32_bf16 v[130:133], v[134:137], v[194:197], v[130:133]
	v_mfma_f32_16x16x32_bf16 v[130:133], v[148:151], v[198:201], v[130:133]
	v_mfma_f32_16x16x32_bf16 v[122:125], v[152:155], v[194:197], v[122:125]
	v_mfma_f32_16x16x32_bf16 v[122:125], v[156:159], v[198:201], v[122:125]
	v_mfma_f32_16x16x32_bf16 v[114:117], v[134:137], v[202:205], v[114:117]
	v_mfma_f32_16x16x32_bf16 v[114:117], v[148:151], v[206:209], v[114:117]
	v_mfma_f32_16x16x32_bf16 v[106:109], v[152:155], v[202:205], v[106:109]
	v_mfma_f32_16x16x32_bf16 v[106:109], v[156:159], v[206:209], v[106:109]
	v_mfma_f32_16x16x32_bf16 v[98:101], v[134:137], v[210:213], v[98:101]
	v_mfma_f32_16x16x32_bf16 v[98:101], v[148:151], v[214:217], v[98:101]
	v_mfma_f32_16x16x32_bf16 v[90:93], v[152:155], v[210:213], v[90:93]
	v_mfma_f32_16x16x32_bf16 v[90:93], v[156:159], v[214:217], v[90:93]
	v_mfma_f32_16x16x32_bf16 v[82:85], v[134:137], v[218:221], v[82:85]
	v_mfma_f32_16x16x32_bf16 v[82:85], v[148:151], v[222:225], v[82:85]
	v_mfma_f32_16x16x32_bf16 v[74:77], v[152:155], v[218:221], v[74:77]
	v_mfma_f32_16x16x32_bf16 v[74:77], v[156:159], v[222:225], v[74:77]
	v_mfma_f32_16x16x32_bf16 v[126:129], v[160:163], v[194:197], v[126:129]
	v_mfma_f32_16x16x32_bf16 v[126:129], v[182:185], v[198:201], v[126:129]
	v_mfma_f32_16x16x32_bf16 v[118:121], v[186:189], v[194:197], v[118:121]
	v_mfma_f32_16x16x32_bf16 v[118:121], v[190:193], v[198:201], v[118:121]
	v_mfma_f32_16x16x32_bf16 v[110:113], v[160:163], v[202:205], v[110:113]
	v_mfma_f32_16x16x32_bf16 v[110:113], v[182:185], v[206:209], v[110:113]
	v_mfma_f32_16x16x32_bf16 v[102:105], v[186:189], v[202:205], v[102:105]
	v_mfma_f32_16x16x32_bf16 v[102:105], v[190:193], v[206:209], v[102:105]
	v_mfma_f32_16x16x32_bf16 v[94:97], v[160:163], v[210:213], v[94:97]
	v_mfma_f32_16x16x32_bf16 v[94:97], v[182:185], v[214:217], v[94:97]
	v_mfma_f32_16x16x32_bf16 v[86:89], v[186:189], v[210:213], v[86:89]
	v_mfma_f32_16x16x32_bf16 v[86:89], v[190:193], v[214:217], v[86:89]
	v_mfma_f32_16x16x32_bf16 v[78:81], v[160:163], v[218:221], v[78:81]
	v_mfma_f32_16x16x32_bf16 v[78:81], v[182:185], v[222:225], v[78:81]
	v_mfma_f32_16x16x32_bf16 v[70:73], v[186:189], v[218:221], v[70:73]
	v_mfma_f32_16x16x32_bf16 v[70:73], v[190:193], v[222:225], v[70:73]
	s_barrier
	s_setprio 0
	s_add_i32 s41, s41, s13
	v_lshl_add_u64 v[226:227], s[20:21], 0, v[0:1]
	s_mov_b32 m0, s41
	ds_read_b128 v[194:197], v175 offset:16384
	ds_read_b128 v[198:201], v175 offset:17408
	ds_read_b128 v[202:205], v175 offset:18432
	ds_read_b128 v[206:209], v175 offset:19456
	ds_read_b128 v[210:213], v175 offset:20480
	ds_read_b128 v[214:217], v175 offset:21504
	ds_read_b128 v[218:221], v175 offset:22528
	ds_read_b128 v[222:225], v175 offset:23552
	global_load_lds_dwordx4 v[226:227], off
	s_add_i32 m0, s41, 0x2000
	s_add_u32 s42, s20, 0x40000
	v_lshl_add_u64 v[228:229], s[20:21], 0, v[14:15]
	s_addc_u32 s43, s21, 0
	s_add_i32 s41, s44, s13
	global_load_lds_dwordx4 v[228:229], off
	v_lshl_add_u64 v[230:231], s[42:43], 0, v[0:1]
	s_mov_b32 m0, s41
	v_lshl_add_u64 v[232:233], s[22:23], 0, v[138:139]
	global_load_lds_dwordx4 v[230:231], off
	v_lshl_add_u64 v[230:231], s[42:43], 0, v[14:15]
	s_add_i32 m0, s41, 0x2000
	s_nop 0
	global_load_lds_dwordx4 v[230:231], off
	v_lshl_add_u64 v[230:231], s[22:23], 0, v[140:141]
	s_mov_b32 m0, s26
	s_nop 0
	global_load_lds_dwordx4 v[230:231], off
	s_mov_b32 m0, s27
	s_nop 0
	global_load_lds_dwordx4 v[232:233], off
	s_cmp_eq_i32 s40, -2
	s_cselect_b32 s98, s2, 0
	s_cmp_lg_u32 s98, 0
	s_cbranch_scc1 .Lg3_relax_w2
	s_waitcnt vmcnt(8)
	s_branch .Lg3_join_w2

.Lg3_join_w2:
	s_waitcnt lgkmcnt(0)
	s_setprio 1
	s_barrier
	v_mfma_f32_16x16x32_bf16 v[66:69], v[134:137], v[194:197], v[66:69]
	v_mfma_f32_16x16x32_bf16 v[66:69], v[148:151], v[198:201], v[66:69]
	v_mfma_f32_16x16x32_bf16 v[58:61], v[152:155], v[194:197], v[58:61]
	v_mfma_f32_16x16x32_bf16 v[58:61], v[156:159], v[198:201], v[58:61]
	v_mfma_f32_16x16x32_bf16 v[50:53], v[134:137], v[202:205], v[50:53]
	v_mfma_f32_16x16x32_bf16 v[50:53], v[148:151], v[206:209], v[50:53]
	v_mfma_f32_16x16x32_bf16 v[42:45], v[152:155], v[202:205], v[42:45]
	v_mfma_f32_16x16x32_bf16 v[42:45], v[156:159], v[206:209], v[42:45]
	v_mfma_f32_16x16x32_bf16 v[34:37], v[134:137], v[210:213], v[34:37]
	v_mfma_f32_16x16x32_bf16 v[34:37], v[148:151], v[214:217], v[34:37]
	v_mfma_f32_16x16x32_bf16 v[26:29], v[152:155], v[210:213], v[26:29]
	v_mfma_f32_16x16x32_bf16 v[26:29], v[156:159], v[214:217], v[26:29]
	v_mfma_f32_16x16x32_bf16 v[18:21], v[134:137], v[218:221], v[18:21]
	v_mfma_f32_16x16x32_bf16 v[18:21], v[148:151], v[222:225], v[18:21]
	v_mfma_f32_16x16x32_bf16 v[6:9], v[152:155], v[218:221], v[6:9]
	v_mfma_f32_16x16x32_bf16 v[6:9], v[156:159], v[222:225], v[6:9]
	v_mfma_f32_16x16x32_bf16 v[62:65], v[160:163], v[194:197], v[62:65]
	v_mfma_f32_16x16x32_bf16 v[62:65], v[182:185], v[198:201], v[62:65]
	v_mfma_f32_16x16x32_bf16 v[54:57], v[186:189], v[194:197], v[54:57]
	v_mfma_f32_16x16x32_bf16 v[54:57], v[190:193], v[198:201], v[54:57]
	v_mfma_f32_16x16x32_bf16 v[46:49], v[160:163], v[202:205], v[46:49]
	v_mfma_f32_16x16x32_bf16 v[46:49], v[182:185], v[206:209], v[46:49]
	v_mfma_f32_16x16x32_bf16 v[38:41], v[186:189], v[202:205], v[38:41]
	v_mfma_f32_16x16x32_bf16 v[38:41], v[190:193], v[206:209], v[38:41]
	v_mfma_f32_16x16x32_bf16 v[30:33], v[160:163], v[210:213], v[30:33]
	v_mfma_f32_16x16x32_bf16 v[30:33], v[182:185], v[214:217], v[30:33]
	v_mfma_f32_16x16x32_bf16 v[22:25], v[186:189], v[210:213], v[22:25]
	v_mfma_f32_16x16x32_bf16 v[22:25], v[190:193], v[214:217], v[22:25]
	v_mfma_f32_16x16x32_bf16 v[10:13], v[160:163], v[218:221], v[10:13]
	v_mfma_f32_16x16x32_bf16 v[10:13], v[182:185], v[222:225], v[10:13]
	v_mfma_f32_16x16x32_bf16 v[2:5], v[186:189], v[218:221], v[2:5]
	v_mfma_f32_16x16x32_bf16 v[2:5], v[190:193], v[222:225], v[2:5]
	s_barrier
	s_setprio 0
	s_add_i32 s41, 0, 0x18000
	s_add_i32 s42, 0, 0x1c000
	v_add_u32_e32 v156, s41, v171
	v_add_u32_e32 v164, s42, v171
	ds_read_b128 v[134:137], v156
	ds_read_b128 v[148:151], v156 offset:1024
	ds_read_b128 v[152:155], v156 offset:2048
	ds_read_b128 v[156:159], v156 offset:3072
	ds_read_b128 v[160:163], v164
	ds_read_b128 v[182:185], v164 offset:1024
	ds_read_b128 v[186:189], v164 offset:2048
	ds_read_b128 v[190:193], v164 offset:3072
	s_add_u32 s22, s22, 0x40000
	s_addc_u32 s23, s23, 0
	s_mov_b32 m0, s28
	v_lshl_add_u64 v[234:235], s[22:23], 0, v[140:141]
	ds_read_b128 v[194:197], v175 offset:32768
	ds_read_b128 v[198:201], v175 offset:33792
	ds_read_b128 v[202:205], v175 offset:34816
	ds_read_b128 v[206:209], v175 offset:35840
	ds_read_b128 v[210:213], v175 offset:36864
	ds_read_b128 v[214:217], v175 offset:37888
	ds_read_b128 v[218:221], v175 offset:38912
	ds_read_b128 v[222:225], v175 offset:39936
	global_load_lds_dwordx4 v[234:235], off
	v_lshl_add_u64 v[234:235], s[22:23], 0, v[138:139]
	s_mov_b32 m0, s29
	s_nop 0
	global_load_lds_dwordx4 v[234:235], off
	s_waitcnt vmcnt(8)
	s_waitcnt lgkmcnt(0)
	s_setprio 1
	s_barrier
	v_mfma_f32_16x16x32_bf16 v[130:133], v[134:137], v[194:197], v[130:133]
	v_mfma_f32_16x16x32_bf16 v[130:133], v[148:151], v[198:201], v[130:133]
	v_mfma_f32_16x16x32_bf16 v[122:125], v[152:155], v[194:197], v[122:125]
	v_mfma_f32_16x16x32_bf16 v[122:125], v[156:159], v[198:201], v[122:125]
	v_mfma_f32_16x16x32_bf16 v[114:117], v[134:137], v[202:205], v[114:117]
	v_mfma_f32_16x16x32_bf16 v[114:117], v[148:151], v[206:209], v[114:117]
	v_mfma_f32_16x16x32_bf16 v[106:109], v[152:155], v[202:205], v[106:109]
	v_mfma_f32_16x16x32_bf16 v[106:109], v[156:159], v[206:209], v[106:109]
	v_mfma_f32_16x16x32_bf16 v[98:101], v[134:137], v[210:213], v[98:101]
	v_mfma_f32_16x16x32_bf16 v[98:101], v[148:151], v[214:217], v[98:101]
	v_mfma_f32_16x16x32_bf16 v[90:93], v[152:155], v[210:213], v[90:93]
	v_mfma_f32_16x16x32_bf16 v[90:93], v[156:159], v[214:217], v[90:93]
	v_mfma_f32_16x16x32_bf16 v[82:85], v[134:137], v[218:221], v[82:85]
	v_mfma_f32_16x16x32_bf16 v[82:85], v[148:151], v[222:225], v[82:85]
	v_mfma_f32_16x16x32_bf16 v[74:77], v[152:155], v[218:221], v[74:77]
	v_mfma_f32_16x16x32_bf16 v[74:77], v[156:159], v[222:225], v[74:77]
	v_mfma_f32_16x16x32_bf16 v[126:129], v[160:163], v[194:197], v[126:129]
	v_mfma_f32_16x16x32_bf16 v[126:129], v[182:185], v[198:201], v[126:129]
	v_mfma_f32_16x16x32_bf16 v[118:121], v[186:189], v[194:197], v[118:121]
	v_mfma_f32_16x16x32_bf16 v[118:121], v[190:193], v[198:201], v[118:121]
	v_mfma_f32_16x16x32_bf16 v[110:113], v[160:163], v[202:205], v[110:113]
	v_mfma_f32_16x16x32_bf16 v[110:113], v[182:185], v[206:209], v[110:113]
	v_mfma_f32_16x16x32_bf16 v[102:105], v[186:189], v[202:205], v[102:105]
	v_mfma_f32_16x16x32_bf16 v[102:105], v[190:193], v[206:209], v[102:105]
	v_mfma_f32_16x16x32_bf16 v[94:97], v[160:163], v[210:213], v[94:97]
	v_mfma_f32_16x16x32_bf16 v[94:97], v[182:185], v[214:217], v[94:97]
	v_mfma_f32_16x16x32_bf16 v[86:89], v[186:189], v[210:213], v[86:89]
	v_mfma_f32_16x16x32_bf16 v[86:89], v[190:193], v[214:217], v[86:89]
	v_mfma_f32_16x16x32_bf16 v[78:81], v[160:163], v[218:221], v[78:81]
	v_mfma_f32_16x16x32_bf16 v[78:81], v[182:185], v[222:225], v[78:81]
	v_mfma_f32_16x16x32_bf16 v[70:73], v[186:189], v[218:221], v[70:73]
	v_mfma_f32_16x16x32_bf16 v[70:73], v[190:193], v[222:225], v[70:73]
	s_barrier
	s_setprio 0
	s_add_i32 s22, s41, s13
	v_lshl_add_u64 v[226:227], v[226:227], 0, s[92:93]
	s_mov_b32 m0, s22
	ds_read_b128 v[194:197], v175 offset:49152
	ds_read_b128 v[198:201], v175 offset:50176
	ds_read_b128 v[202:205], v175 offset:51200
	ds_read_b128 v[206:209], v175 offset:52224
	ds_read_b128 v[210:213], v175 offset:53248
	ds_read_b128 v[214:217], v175 offset:54272
	ds_read_b128 v[218:221], v175 offset:55296
	ds_read_b128 v[222:225], v175 offset:56320
	global_load_lds_dwordx4 v[226:227], off
	s_add_i32 m0, s22, 0x2000
	s_add_u32 s20, s20, 0x40080
	v_lshl_add_u64 v[226:227], v[228:229], 0, s[92:93]
	s_addc_u32 s21, s21, 0
	s_add_i32 s22, s42, s13
	global_load_lds_dwordx4 v[226:227], off
	v_lshl_add_u64 v[226:227], s[20:21], 0, v[0:1]
	s_mov_b32 m0, s22
	s_nop 0
	global_load_lds_dwordx4 v[226:227], off
	v_lshl_add_u64 v[226:227], s[20:21], 0, v[14:15]
	s_add_i32 m0, s22, 0x2000
	s_nop 0
	global_load_lds_dwordx4 v[226:227], off
	v_lshl_add_u64 v[226:227], v[230:231], 0, s[92:93]
	s_mov_b32 m0, s30
	s_nop 0
	global_load_lds_dwordx4 v[226:227], off
	v_lshl_add_u64 v[226:227], v[232:233], 0, s[92:93]
	s_mov_b32 m0, s31
	s_nop 0
	global_load_lds_dwordx4 v[226:227], off
	s_waitcnt vmcnt(8)
	s_waitcnt lgkmcnt(0)
	s_setprio 1
	s_barrier
	v_mfma_f32_16x16x32_bf16 v[66:69], v[134:137], v[194:197], v[66:69]
	v_mfma_f32_16x16x32_bf16 v[66:69], v[148:151], v[198:201], v[66:69]
	v_mfma_f32_16x16x32_bf16 v[58:61], v[152:155], v[194:197], v[58:61]
	v_mfma_f32_16x16x32_bf16 v[58:61], v[156:159], v[198:201], v[58:61]
	v_mfma_f32_16x16x32_bf16 v[50:53], v[134:137], v[202:205], v[50:53]
	v_mfma_f32_16x16x32_bf16 v[50:53], v[148:151], v[206:209], v[50:53]
	v_mfma_f32_16x16x32_bf16 v[42:45], v[152:155], v[202:205], v[42:45]
	v_mfma_f32_16x16x32_bf16 v[42:45], v[156:159], v[206:209], v[42:45]
	v_mfma_f32_16x16x32_bf16 v[34:37], v[134:137], v[210:213], v[34:37]
	v_mfma_f32_16x16x32_bf16 v[34:37], v[148:151], v[214:217], v[34:37]
	v_mfma_f32_16x16x32_bf16 v[26:29], v[152:155], v[210:213], v[26:29]
	v_mfma_f32_16x16x32_bf16 v[26:29], v[156:159], v[214:217], v[26:29]
	v_mfma_f32_16x16x32_bf16 v[18:21], v[134:137], v[218:221], v[18:21]
	v_mfma_f32_16x16x32_bf16 v[18:21], v[148:151], v[222:225], v[18:21]
	v_mfma_f32_16x16x32_bf16 v[6:9], v[152:155], v[218:221], v[6:9]
	v_mfma_f32_16x16x32_bf16 v[6:9], v[156:159], v[222:225], v[6:9]
	v_mfma_f32_16x16x32_bf16 v[62:65], v[160:163], v[194:197], v[62:65]
	v_mfma_f32_16x16x32_bf16 v[62:65], v[182:185], v[198:201], v[62:65]
	v_mfma_f32_16x16x32_bf16 v[54:57], v[186:189], v[194:197], v[54:57]
	v_mfma_f32_16x16x32_bf16 v[54:57], v[190:193], v[198:201], v[54:57]
	v_mfma_f32_16x16x32_bf16 v[46:49], v[160:163], v[202:205], v[46:49]
	v_mfma_f32_16x16x32_bf16 v[46:49], v[182:185], v[206:209], v[46:49]
	v_mfma_f32_16x16x32_bf16 v[38:41], v[186:189], v[202:205], v[38:41]
	v_mfma_f32_16x16x32_bf16 v[38:41], v[190:193], v[206:209], v[38:41]
	v_mfma_f32_16x16x32_bf16 v[30:33], v[160:163], v[210:213], v[30:33]
	v_mfma_f32_16x16x32_bf16 v[30:33], v[182:185], v[214:217], v[30:33]
	v_mfma_f32_16x16x32_bf16 v[22:25], v[186:189], v[210:213], v[22:25]
	v_mfma_f32_16x16x32_bf16 v[22:25], v[190:193], v[214:217], v[22:25]
	v_mfma_f32_16x16x32_bf16 v[10:13], v[160:163], v[218:221], v[10:13]
	v_mfma_f32_16x16x32_bf16 v[10:13], v[182:185], v[222:225], v[10:13]
	v_mfma_f32_16x16x32_bf16 v[2:5], v[186:189], v[218:221], v[2:5]
	v_mfma_f32_16x16x32_bf16 v[2:5], v[190:193], v[222:225], v[2:5]
	s_barrier
	s_setprio 0
	s_add_i32 s40, s40, 2
	s_add_u32 s4, s4, 0x100
	s_addc_u32 s5, s5, 0
	s_add_u32 s38, s38, 0x100
	s_addc_u32 s39, s39, 0
	s_cmp_gt_u32 s40, 13
	s_cbranch_scc0 .LBB0_893
